# v55 plus the lagging group's per-unit re-skew barrier moved from the unit-loop latch to the end of the unit header (its header runs under the leader's header + first load section)
# speedup vs baseline: 1.0014x; 1.0014x over previous
;     __device__ __forceinline__ size_t aoff(const Unit& u) const { return (size_t)u.pm * bm * lda * 2; }
;     __device__ __forceinline__ size_t boff(const Unit& u) const { return (size_t)u.pn * BM * ldb * 2; }
;     __device__ __forceinline__ size_t aoff(const Unit& u) const { return ((size_t)u.pm * BM * lda + (size_t)u.pn * akoff) * 2; }
;     __device__ __forceinline__ size_t boff(const Unit& u) const { return (size_t)u.pn * BM * ldb * 2; }
;     __device__ __forceinline__ size_t aoff(const Unit& u) const { return ((size_t)u.pm * BM * lda + (size_t)(u.pn >> 1) * akoff) * 2; }
;     __device__ __forceinline__ size_t boff(const Unit& u) const { return (size_t)u.pn * BM * ldb * 2; }
; #define PG8_STAGE(bufoff, gbase, voff) do { _Pragma("unroll") for (int _i = 0; _i < 2; ++_i) \
;         __builtin_amdgcn_global_load_lds((const unsigned*)((const char*)(gbase) + (voff)[_i]), (LAS unsigned*)(lds + (bufoff) + ldsw + _i * 8192), 16, 0, 0); } while (0)
; #define PG8_LDB(dst, b, h) do { _Pragma("unroll") for (int n = 0; n < 2; ++n) _Pragma("unroll") for (int k = 0; k < 2; ++k) dst[n][k] = *(const LAS bf16x8*)(lds + PG8_SB(b, h) + boff + n * 2048 + k * 1024); } while (0)
;     ...
;         const bool has_next = S.next(ui + 1, nxt);
;         const char* nA = has_next ? (const char*)g.A + S.aoff(nxt) : cA; const char* nB = has_next ? (const char*)g.Bt + S.boff(nxt) : cB;
;         if constexpr (Epi::PRE) E.pre(lds, cur, wid);
;         for (int t = 0; t < nt; t += 2) {
;             const bool last = (t == nt - 2);
;             const char* a1 = cA + (size_t)(t + 1) * kstep;
;             const char* a2 = last ? nA : cA + (size_t)(t + 2) * kstep; const char* b2 = last ? nB : cB + (size_t)(t + 2) * kstep;
;             const char* a3 = a2 + kstep; const char* b3 = b2 + kstep;
;             if constexpr (SP2) {
;             PG8_LDB(B0, 0, 0); PG8_LDB(B1, 0, 1); PG8_SCHED; PG8_LDA(At, 0, 0); PG8_STAGE(PG8_SA(1, 1), a1 + hstepA, voffA);
;             PG8_WAIT_V(8); PG8_WAIT_L(0); PG8_BAR; PG8_MMA(0, 0, At, B0); PG8_MMA(0, 1, At, B1); PG8_BAR; PG8_SCHED;
;             PG8_LDA(At, 0, 1); PG8_STAGE(PG8_SB(0, 0), b2, voffB); PG8_STAGE(PG8_SB(0, 1), b2 + hstepB, voffB); PG8_STAGE(PG8_SA(0, 0), a2, voffA);
;             PG8_WAIT_V(8); PG8_WAIT_L(0); PG8_BAR; PG8_MMA(1, 0, At, B0); PG8_MMA(1, 1, At, B1); PG8_BAR; PG8_SCHED;
;     ...
;         if constexpr (ALIGN_EPI) { if (wr == 1) PG8_BAR; }
.LBB0_199:
	s_ashr_i32 s23, s22, 31
	s_lshl_b64 s[2:3], s[22:23], 20
	s_add_u32 s24, s33, s2
	s_addc_u32 s25, s36, s3
	s_and_b64 s[2:3], s[4:5], exec
	s_cselect_b32 s2, s25, s29
	s_cselect_b32 s3, s24, s28
	s_ashr_i32 s21, s20, 31
	s_lshl_b64 s[26:27], s[20:21], 20
	s_add_u32 s26, s37, s26
	s_addc_u32 s27, s38, s27
	s_and_b64 s[34:35], s[4:5], exec
	s_cselect_b32 s9, s27, s31
	s_cselect_b32 s21, s26, s30
	s_add_u32 s28, s28, 0x80080
	s_addc_u32 s29, s29, 0
	s_add_u32 s23, s30, 0x100
	s_addc_u32 s54, s31, 0
	s_mov_b32 s56, -2
	s_waitcnt vmcnt(5)
	s_cmp_lt_u32 s70, 2
	s_cbranch_scc1 .Lyb_ic
	s_cmp_eq_u64 s[14:15], 0
	s_cbranch_scc0 .Lyb_ic
	s_barrier
.Lyb_ic:
	ds_read_b128 v[26:29], v172
	ds_read_b128 v[30:33], v172 offset:1024
	ds_read_b128 v[42:45], v172 offset:2048
	ds_read_b128 v[46:49], v172 offset:3072
	ds_read_b128 v[146:149], v173
	ds_read_b128 v[150:153], v173 offset:1024
	ds_read_b128 v[164:167], v173 offset:2048
	ds_read_b128 v[168:171], v173 offset:3072
	s_add_u32 s30, s28, 0xfff80080
	s_addc_u32 s31, s29, -1
	s_cmp_eq_u32 s56, 28
	s_cselect_b32 s35, s2, s31
	s_cselect_b32 s34, s3, s30
	s_cselect_b32 s31, s9, s54
	s_cselect_b32 s30, s21, s23
	s_cselect_b32 s100, -1, 0
	s_andn2_b32 s100, s100, s101
	s_add_i32 m0, s43, 0xc000
	ds_read_b128 v[178:181], v174
	ds_read_b128 v[182:185], v174 offset:1024
	ds_read_b128 v[186:189], v174 offset:2048
	ds_read_b128 v[190:193], v174 offset:3072
	ds_read_b128 v[194:197], v174 offset:4096
	ds_read_b128 v[198:201], v174 offset:5120
	ds_read_b128 v[202:205], v174 offset:6144
	ds_read_b128 v[206:209], v174 offset:7168
	global_load_lds_dwordx4 v160, s[28:29]
	s_add_i32 m0, s43, 0xe000
	s_nop 0
	global_load_lds_dwordx4 v162, s[28:29]
	s_waitcnt vmcnt(8)
	s_waitcnt lgkmcnt(0)
	s_setprio 1
	s_barrier
	v_mfma_f32_16x16x32_bf16 v[142:145], v[26:29], v[178:181], 0
	v_mfma_f32_16x16x32_bf16 v[138:141], v[42:45], v[178:181], 0
	v_mfma_f32_16x16x32_bf16 v[126:129], v[26:29], v[186:189], 0
	v_mfma_f32_16x16x32_bf16 v[122:125], v[42:45], v[186:189], 0
	v_mfma_f32_16x16x32_bf16 v[110:113], v[26:29], v[194:197], 0
	v_mfma_f32_16x16x32_bf16 v[106:109], v[42:45], v[194:197], 0
	v_mfma_f32_16x16x32_bf16 v[94:97], v[26:29], v[202:205], 0
	v_mfma_f32_16x16x32_bf16 v[90:93], v[42:45], v[202:205], 0
	v_mfma_f32_16x16x32_bf16 v[142:145], v[30:33], v[182:185], v[142:145]
	v_mfma_f32_16x16x32_bf16 v[138:141], v[46:49], v[182:185], v[138:141]
	v_mfma_f32_16x16x32_bf16 v[126:129], v[30:33], v[190:193], v[126:129]
	v_mfma_f32_16x16x32_bf16 v[122:125], v[46:49], v[190:193], v[122:125]
	v_mfma_f32_16x16x32_bf16 v[110:113], v[30:33], v[198:201], v[110:113]
	v_mfma_f32_16x16x32_bf16 v[106:109], v[46:49], v[198:201], v[106:109]
	v_mfma_f32_16x16x32_bf16 v[94:97], v[30:33], v[206:209], v[94:97]
	v_mfma_f32_16x16x32_bf16 v[90:93], v[46:49], v[206:209], v[90:93]
	s_setprio 0
	s_setprio 1
	v_mfma_f32_16x16x32_bf16 v[134:137], v[146:149], v[178:181], 0
	v_mfma_f32_16x16x32_bf16 v[130:133], v[164:167], v[178:181], 0
	v_mfma_f32_16x16x32_bf16 v[118:121], v[146:149], v[186:189], 0
	v_mfma_f32_16x16x32_bf16 v[114:117], v[164:167], v[186:189], 0
	v_mfma_f32_16x16x32_bf16 v[102:105], v[146:149], v[194:197], 0
	v_mfma_f32_16x16x32_bf16 v[98:101], v[164:167], v[194:197], 0
	v_mfma_f32_16x16x32_bf16 v[86:89], v[146:149], v[202:205], 0
	v_mfma_f32_16x16x32_bf16 v[82:85], v[164:167], v[202:205], 0
	v_mfma_f32_16x16x32_bf16 v[134:137], v[150:153], v[182:185], v[134:137]
	v_mfma_f32_16x16x32_bf16 v[130:133], v[168:171], v[182:185], v[130:133]
	v_mfma_f32_16x16x32_bf16 v[118:121], v[150:153], v[190:193], v[118:121]
	v_mfma_f32_16x16x32_bf16 v[114:117], v[168:171], v[190:193], v[114:117]
	v_mfma_f32_16x16x32_bf16 v[102:105], v[150:153], v[198:201], v[102:105]
	v_mfma_f32_16x16x32_bf16 v[98:101], v[168:171], v[198:201], v[98:101]
	v_mfma_f32_16x16x32_bf16 v[86:89], v[150:153], v[206:209], v[86:89]
	v_mfma_f32_16x16x32_bf16 v[82:85], v[168:171], v[206:209], v[82:85]
	s_barrier
	s_setprio 0
	s_mov_b32 m0, s39
	v_lshl_add_u64 v[210:211], s[30:31], 0, v[0:1]
	s_add_u32 s72, s30, 0x80000
	s_addc_u32 s73, s31, 0
	ds_read_b128 v[178:181], v174 offset:16384
	ds_read_b128 v[182:185], v174 offset:17408
	ds_read_b128 v[186:189], v174 offset:18432
	ds_read_b128 v[190:193], v174 offset:19456
	ds_read_b128 v[194:197], v174 offset:20480
	ds_read_b128 v[198:201], v174 offset:21504
	ds_read_b128 v[202:205], v174 offset:22528
	ds_read_b128 v[206:209], v174 offset:23552
	s_cmp_lg_u32 s100, 0
	s_cbranch_scc1 .Ltl_ic_0s_p
	global_load_lds_dwordx4 v0, s[30:31]
	v_lshl_add_u64 v[212:213], s[30:31], 0, v[158:159]
	s_mov_b32 m0, s40
	s_nop 0
	global_load_lds_dwordx4 v158, s[30:31]
	s_mov_b32 m0, s41
	v_lshl_add_u64 v[216:217], s[34:35], 0, v[156:157]
	global_load_lds_dwordx4 v0, s[72:73]
	s_mov_b32 m0, s42
	s_nop 0
	global_load_lds_dwordx4 v158, s[72:73]
	v_lshl_add_u64 v[214:215], s[34:35], 0, v[154:155]
	s_mov_b32 m0, s43
	s_nop 0
	global_load_lds_dwordx4 v154, s[34:35]
	s_mov_b32 m0, s44
	s_nop 0
	global_load_lds_dwordx4 v156, s[34:35]
	s_waitcnt vmcnt(8)
	s_branch .Ltl_ic_0d_p

; #define PG8_BAR __builtin_amdgcn_s_barrier()
;     ...
;         cur = nxt; cA = nA; cB = nB; ++ui; cur.par = ui & 1;
;         if constexpr (ALIGN_EPI) { if (wr == 1) PG8_BAR; }
.LBB0_318:
	s_andn2_b64 vcc, exec, s[10:11]
	s_cbranch_vccnz .LBB0_193
	s_branch .LBB0_193

;     __device__ __forceinline__ size_t aoff(const Unit& u) const { return (size_t)u.pm * bm * lda * 2; }
;     __device__ __forceinline__ size_t boff(const Unit& u) const { return (size_t)u.pn * BM * ldb * 2; }
;     __device__ __forceinline__ size_t aoff(const Unit& u) const { return ((size_t)u.pm * BM * lda + (size_t)u.pn * akoff) * 2; }
;     __device__ __forceinline__ size_t boff(const Unit& u) const { return (size_t)u.pn * BM * ldb * 2; }
;     __device__ __forceinline__ size_t aoff(const Unit& u) const { return ((size_t)u.pm * BM * lda + (size_t)(u.pn >> 1) * akoff) * 2; }
;     __device__ __forceinline__ size_t boff(const Unit& u) const { return (size_t)u.pn * BM * ldb * 2; }
; #define PG8_STAGE(bufoff, gbase, voff) do { _Pragma("unroll") for (int _i = 0; _i < 2; ++_i) \
;         __builtin_amdgcn_global_load_lds((const unsigned*)((const char*)(gbase) + (voff)[_i]), (LAS unsigned*)(lds + (bufoff) + ldsw + _i * 8192), 16, 0, 0); } while (0)
; #define PG8_LDB(dst, b, h) do { _Pragma("unroll") for (int n = 0; n < 2; ++n) _Pragma("unroll") for (int k = 0; k < 2; ++k) dst[n][k] = *(const LAS bf16x8*)(lds + PG8_SB(b, h) + boff + n * 2048 + k * 1024); } while (0)
;     ...
;         const bool has_next = S.next(ui + 1, nxt);
;         const char* nA = has_next ? (const char*)g.A + S.aoff(nxt) : cA; const char* nB = has_next ? (const char*)g.Bt + S.boff(nxt) : cB;
;         if constexpr (Epi::PRE) E.pre(lds, cur, wid);
;         for (int t = 0; t < nt; t += 2) {
;             const bool last = (t == nt - 2);
;             const char* a1 = cA + (size_t)(t + 1) * kstep;
;             const char* a2 = last ? nA : cA + (size_t)(t + 2) * kstep; const char* b2 = last ? nB : cB + (size_t)(t + 2) * kstep;
;             const char* a3 = a2 + kstep; const char* b3 = b2 + kstep;
;             if constexpr (SP2) {
;             PG8_LDB(B0, 0, 0); PG8_LDB(B1, 0, 1); PG8_SCHED; PG8_LDA(At, 0, 0); PG8_STAGE(PG8_SA(1, 1), a1 + hstepA, voffA);
;             PG8_WAIT_V(8); PG8_WAIT_L(0); PG8_BAR; PG8_MMA(0, 0, At, B0); PG8_MMA(0, 1, At, B1); PG8_BAR; PG8_SCHED;
;             PG8_LDA(At, 0, 1); PG8_STAGE(PG8_SB(0, 0), b2, voffB); PG8_STAGE(PG8_SB(0, 1), b2 + hstepB, voffB); PG8_STAGE(PG8_SA(0, 0), a2, voffA);
;             PG8_WAIT_V(8); PG8_WAIT_L(0); PG8_BAR; PG8_MMA(1, 0, At, B0); PG8_MMA(1, 1, At, B1); PG8_BAR; PG8_SCHED;
;     ...
;         if constexpr (ALIGN_EPI) { if (wr == 1) PG8_BAR; }
.LBB0_702:
	s_ashr_i32 s29, s28, 31
	s_lshl_b64 s[2:3], s[28:29], 20
	s_add_u32 s30, s33, s2
	s_addc_u32 s31, s47, s3
	s_and_b64 s[2:3], s[4:5], exec
	s_cselect_b32 s2, s31, s11
	s_cselect_b32 s3, s30, s10
	s_ashr_i32 s27, s26, 31
	s_lshl_b64 s[34:35], s[26:27], 20
	s_add_u32 s34, s48, s34
	s_addc_u32 s35, s49, s35
	s_and_b64 s[36:37], s[4:5], exec
	s_cselect_b32 s9, s35, s13
	s_cselect_b32 s27, s34, s12
	s_add_u32 s10, s10, 0x80080
	s_addc_u32 s11, s11, 0
	s_add_u32 s29, s12, 0x100
	s_addc_u32 s38, s13, 0
	s_mov_b32 s39, -2
	s_cmp_lt_u32 s23, 2
	s_cbranch_scc1 .Lyb_ia
	s_cmp_eq_u64 s[18:19], 0
	s_cbranch_scc0 .Lyb_ia
	s_barrier
.Lyb_ia:
	v_add_u32_e32 v0, s50, v146
	ds_read_b128 v[138:141], v0
	ds_read_b128 v[142:145], v0 offset:1024
	ds_read_b128 v[148:151], v0 offset:2048
	ds_read_b128 v[152:155], v0 offset:3072
	v_add_u32_e32 v0, s54, v146
	ds_read_b128 v[156:159], v0
	ds_read_b128 v[160:163], v0 offset:1024
	ds_read_b128 v[164:167], v0 offset:2048
	ds_read_b128 v[168:171], v0 offset:3072
	s_add_u32 s12, s10, 0xfff80080
	s_addc_u32 s13, s11, -1
	s_cmp_eq_u32 s39, 28
	s_cselect_b32 s37, s2, s13
	s_cselect_b32 s36, s3, s12
	s_cselect_b32 s13, s9, s38
	s_cselect_b32 s12, s27, s29
	s_cselect_b32 s100, -1, 0
	s_andn2_b32 s100, s100, s101
	s_add_i32 m0, s58, 0xc000
	ds_read_b128 v[172:175], v147
	ds_read_b128 v[176:179], v147 offset:1024
	ds_read_b128 v[180:183], v147 offset:2048
	ds_read_b128 v[184:187], v147 offset:3072
	ds_read_b128 v[188:191], v147 offset:4096
	ds_read_b128 v[192:195], v147 offset:5120
	ds_read_b128 v[196:199], v147 offset:6144
	ds_read_b128 v[200:203], v147 offset:7168
	global_load_lds_dwordx4 v134, s[10:11]
	s_add_i32 m0, s58, 0xe000
	s_nop 0
	global_load_lds_dwordx4 v136, s[10:11]
	s_waitcnt vmcnt(8)
	s_waitcnt lgkmcnt(0)
	s_setprio 1
	s_barrier
	v_mfma_f32_16x16x32_bf16 v[126:129], v[138:141], v[172:175], 0
	v_mfma_f32_16x16x32_bf16 v[122:125], v[148:151], v[172:175], 0
	v_mfma_f32_16x16x32_bf16 v[110:113], v[138:141], v[180:183], 0
	v_mfma_f32_16x16x32_bf16 v[106:109], v[148:151], v[180:183], 0
	v_mfma_f32_16x16x32_bf16 v[94:97], v[138:141], v[188:191], 0
	v_mfma_f32_16x16x32_bf16 v[90:93], v[148:151], v[188:191], 0
	v_mfma_f32_16x16x32_bf16 v[78:81], v[138:141], v[196:199], 0
	v_mfma_f32_16x16x32_bf16 v[74:77], v[148:151], v[196:199], 0
	v_mfma_f32_16x16x32_bf16 v[126:129], v[142:145], v[176:179], v[126:129]
	v_mfma_f32_16x16x32_bf16 v[122:125], v[152:155], v[176:179], v[122:125]
	v_mfma_f32_16x16x32_bf16 v[110:113], v[142:145], v[184:187], v[110:113]
	v_mfma_f32_16x16x32_bf16 v[106:109], v[152:155], v[184:187], v[106:109]
	v_mfma_f32_16x16x32_bf16 v[94:97], v[142:145], v[192:195], v[94:97]
	v_mfma_f32_16x16x32_bf16 v[90:93], v[152:155], v[192:195], v[90:93]
	v_mfma_f32_16x16x32_bf16 v[78:81], v[142:145], v[200:203], v[78:81]
	v_mfma_f32_16x16x32_bf16 v[74:77], v[152:155], v[200:203], v[74:77]
	s_setprio 0
	s_setprio 1
	v_mfma_f32_16x16x32_bf16 v[118:121], v[156:159], v[172:175], 0
	v_mfma_f32_16x16x32_bf16 v[114:117], v[164:167], v[172:175], 0
	v_mfma_f32_16x16x32_bf16 v[102:105], v[156:159], v[180:183], 0
	v_mfma_f32_16x16x32_bf16 v[98:101], v[164:167], v[180:183], 0
	v_mfma_f32_16x16x32_bf16 v[86:89], v[156:159], v[188:191], 0
	v_mfma_f32_16x16x32_bf16 v[82:85], v[164:167], v[188:191], 0
	v_mfma_f32_16x16x32_bf16 v[70:73], v[156:159], v[196:199], 0
	v_mfma_f32_16x16x32_bf16 v[66:69], v[164:167], v[196:199], 0
	v_mfma_f32_16x16x32_bf16 v[118:121], v[160:163], v[176:179], v[118:121]
	v_mfma_f32_16x16x32_bf16 v[114:117], v[168:171], v[176:179], v[114:117]
	v_mfma_f32_16x16x32_bf16 v[102:105], v[160:163], v[184:187], v[102:105]
	v_mfma_f32_16x16x32_bf16 v[98:101], v[168:171], v[184:187], v[98:101]
	v_mfma_f32_16x16x32_bf16 v[86:89], v[160:163], v[192:195], v[86:89]
	v_mfma_f32_16x16x32_bf16 v[82:85], v[168:171], v[192:195], v[82:85]
	v_mfma_f32_16x16x32_bf16 v[70:73], v[160:163], v[200:203], v[70:73]
	v_mfma_f32_16x16x32_bf16 v[66:69], v[168:171], v[200:203], v[66:69]
	s_barrier
	s_setprio 0
	s_mov_b32 m0, s51
	v_lshl_add_u64 v[204:205], s[12:13], 0, v[130:131]
	s_add_u32 s40, s12, 0x80000
	s_addc_u32 s41, s13, 0
	ds_read_b128 v[172:175], v147 offset:16384
	ds_read_b128 v[176:179], v147 offset:17408
	ds_read_b128 v[180:183], v147 offset:18432
	ds_read_b128 v[184:187], v147 offset:19456
	ds_read_b128 v[188:191], v147 offset:20480
	ds_read_b128 v[192:195], v147 offset:21504
	ds_read_b128 v[196:199], v147 offset:22528
	ds_read_b128 v[200:203], v147 offset:23552
	s_cmp_lg_u32 s100, 0
	s_cbranch_scc1 .Ltl_ia_0s_p
	global_load_lds_dwordx4 v130, s[12:13]
	v_lshl_add_u64 v[206:207], s[12:13], 0, v[132:133]
	s_mov_b32 m0, s52
	s_nop 0
	global_load_lds_dwordx4 v132, s[12:13]
	s_mov_b32 m0, s56
	v_lshl_add_u64 v[210:211], s[36:37], 0, v[132:133]
	global_load_lds_dwordx4 v130, s[40:41]
	s_mov_b32 m0, s57
	s_nop 0
	global_load_lds_dwordx4 v132, s[40:41]
	v_lshl_add_u64 v[208:209], s[36:37], 0, v[130:131]
	s_mov_b32 m0, s58
	s_nop 0
	global_load_lds_dwordx4 v130, s[36:37]
	s_mov_b32 m0, s59
	s_nop 0
	global_load_lds_dwordx4 v132, s[36:37]
	s_waitcnt vmcnt(8)
	s_branch .Ltl_ia_0d_p

; #define PG8_BAR __builtin_amdgcn_s_barrier()
;     ...
;         cur = nxt; cA = nA; cB = nB; ++ui; cur.par = ui & 1;
;         if constexpr (ALIGN_EPI) { if (wr == 1) PG8_BAR; }
.LBB0_863:
	s_andn2_b64 vcc, exec, s[14:15]
	s_cbranch_vccnz .LBB0_696
	s_branch .LBB0_696

; #define LAS __attribute__((address_space(3)))
; __device__ __forceinline__ int lane_id() { int l; asm volatile("v_mbcnt_lo_u32_b32 %0, -1, 0\n\tv_mbcnt_hi_u32_b32 %0, -1, %0" : "=v"(l)); return l; }
;     __device__ __forceinline__ size_t aoff(const Unit& u) const { return (size_t)u.pm * bm * lda * 2; }
;     __device__ __forceinline__ size_t boff(const Unit& u) const { return (size_t)u.pn * BM * ldb * 2; }
;     __device__ __forceinline__ size_t aoff(const Unit& u) const { return ((size_t)u.pm * BM * lda + (size_t)u.pn * akoff) * 2; }
;     __device__ __forceinline__ size_t boff(const Unit& u) const { return (size_t)u.pn * BM * ldb * 2; }
;     __device__ __forceinline__ size_t aoff(const Unit& u) const { return ((size_t)u.pm * BM * lda + (size_t)(u.pn >> 1) * akoff) * 2; }
; #define PG8_WAIT_V(n) asm volatile("s_waitcnt vmcnt(" #n ")" ::: "memory")
;     ...
;         const bool has_next = S.next(ui + 1, nxt);
;         const char* nA = has_next ? (const char*)g.A + S.aoff(nxt) : cA; const char* nB = has_next ? (const char*)g.Bt + S.boff(nxt) : cB;
;         if constexpr (Epi::PRE) E.pre(lds, cur, wid);
;         for (int t = 0; t < nt; t += 2) {
;             const bool last = (t == nt - 2);
;             const char* a1 = cA + (size_t)(t + 1) * kstep;
;             const char* a2 = last ? nA : cA + (size_t)(t + 2) * kstep; const char* b2 = last ? nB : cB + (size_t)(t + 2) * kstep;
;             const char* a3 = a2 + kstep; const char* b3 = b2 + kstep;
;             if constexpr (SP2) {
;             PG8_LDB(B0, 0, 0); PG8_LDB(B1, 0, 1); PG8_SCHED; PG8_LDA(At, 0, 0); PG8_STAGE(PG8_SA(1, 1), a1 + hstepA, voffA);
;             PG8_WAIT_V(8); PG8_WAIT_L(0); PG8_BAR; PG8_MMA(0, 0, At, B0); PG8_MMA(0, 1, At, B1); PG8_BAR; PG8_SCHED;
;             PG8_LDA(At, 0, 1); PG8_STAGE(PG8_SB(0, 0), b2, voffB); PG8_STAGE(PG8_SB(0, 1), b2 + hstepB, voffB); PG8_STAGE(PG8_SA(0, 0), a2, voffA);
;             PG8_WAIT_V(8); PG8_WAIT_L(0); PG8_BAR; PG8_MMA(1, 0, At, B0); PG8_MMA(1, 1, At, B1); PG8_BAR; PG8_SCHED;
;     __device__ __forceinline__ void pre(LAS unsigned char* l, const pg8::Unit& u, int wid) const {
;         const float* src = (const float*)(ws + WS_SSQQ) + ((size_t)li * 8 + wid) * MT + u.pm * 256 + lane_id() * 4;
;         __builtin_amdgcn_global_load_lds((const unsigned*)src, (LAS unsigned*)(l + EPI_LDS + u.par * 8192 + wid * 1024), 16, 0, 0);
;     }
.LBB0_1191:
	s_ashr_i32 s27, s26, 31
	s_lshl_b64 s[2:3], s[26:27], 18
	s_add_u32 s28, s33, s2
	s_addc_u32 s29, s43, s3
	s_and_b64 s[2:3], s[4:5], exec
	s_cselect_b32 s2, s29, s11
	s_cselect_b32 s3, s28, s10
	s_ashr_i32 s25, s24, 31
	s_lshl_b64 s[30:31], s[24:25], 18
	s_add_u32 s30, s44, s30
	s_addc_u32 s31, s45, s31
	s_and_b64 s[56:57], s[4:5], exec
	s_cselect_b32 s7, s31, s13
	s_cselect_b32 s27, s30, s12
	s_lshl_b32 s8, s8, 8
	s_ashr_i32 s9, s8, 31
	s_lshl_b64 s[56:57], s[8:9], 2
	s_add_u32 s56, s94, s56
	v_mbcnt_lo_u32_b32 v0, -1, 0
	v_mbcnt_hi_u32_b32 v0, -1, v0
	s_addc_u32 s57, s95, s57
	v_lshlrev_b32_e32 v2, 2, v0
	v_ashrrev_i32_e32 v3, 31, v2
	s_lshl_b32 s25, s34, 13
	v_lshl_add_u64 v[2:3], v[2:3], 2, s[56:57]
	s_add_i32 m0, s81, s25
	s_add_u32 s10, s10, 0x20080
	global_load_lds_dwordx4 v[2:3], off
	s_addc_u32 s11, s11, 0
	s_add_u32 s9, s12, 0x100
	s_addc_u32 s52, s13, 0
	s_mov_b32 s54, -2
	s_cmp_lt_u32 s47, 2
	s_cbranch_scc1 .Lyb_q
	s_cmp_eq_u64 s[16:17], 0
	s_cbranch_scc0 .Lyb_q
	s_barrier
.Lyb_q:
	v_add_u32_e32 v0, s49, v216
	ds_read_b128 v[10:13], v0
	ds_read_b128 v[14:17], v0 offset:1024
	ds_read_b128 v[18:21], v0 offset:2048
	ds_read_b128 v[22:25], v0 offset:3072
	v_add_u32_e32 v0, s58, v216
	ds_read_b128 v[26:29], v0
	ds_read_b128 v[30:33], v0 offset:1024
	ds_read_b128 v[42:45], v0 offset:2048
	ds_read_b128 v[46:49], v0 offset:3072
	s_add_u32 s12, s10, 0xfffe0080
	s_addc_u32 s13, s11, -1
	s_cmp_eq_u32 s54, 4
	s_cselect_b32 s35, s2, s13
	s_cselect_b32 s34, s3, s12
	s_cselect_b32 s13, s7, s52
	s_cselect_b32 s12, s27, s9
	s_cselect_b32 s100, -1, 0
	s_andn2_b32 s100, s100, s101
	s_add_i32 m0, s62, 0xc000
	ds_read_b128 v[50:53], v217
	ds_read_b128 v[54:57], v217 offset:1024
	ds_read_b128 v[58:61], v217 offset:2048
	ds_read_b128 v[62:65], v217 offset:3072
	ds_read_b128 v[178:181], v217 offset:4096
	ds_read_b128 v[182:185], v217 offset:5120
	ds_read_b128 v[198:201], v217 offset:6144
	ds_read_b128 v[208:211], v217 offset:7168
	global_load_lds_dwordx4 v194, s[10:11]
	s_add_i32 m0, s62, 0xe000
	s_nop 0
	global_load_lds_dwordx4 v196, s[10:11]
	s_waitcnt vmcnt(8)
	s_waitcnt lgkmcnt(0)
	s_setprio 1
	s_barrier
	v_mfma_f32_16x16x32_bf16 v[38:41], v[10:13], v[50:53], 0
	v_mfma_f32_16x16x32_bf16 v[34:37], v[18:21], v[50:53], 0
	v_mfma_f32_16x16x32_bf16 v[174:177], v[10:13], v[58:61], 0
	v_mfma_f32_16x16x32_bf16 v[170:173], v[18:21], v[58:61], 0
	v_mfma_f32_16x16x32_bf16 v[158:161], v[10:13], v[178:181], 0
	v_mfma_f32_16x16x32_bf16 v[154:157], v[18:21], v[178:181], 0
	v_mfma_f32_16x16x32_bf16 v[142:145], v[10:13], v[198:201], 0
	v_mfma_f32_16x16x32_bf16 v[138:141], v[18:21], v[198:201], 0
	v_mfma_f32_16x16x32_bf16 v[38:41], v[14:17], v[54:57], v[38:41]
	v_mfma_f32_16x16x32_bf16 v[34:37], v[22:25], v[54:57], v[34:37]
	v_mfma_f32_16x16x32_bf16 v[174:177], v[14:17], v[62:65], v[174:177]
	v_mfma_f32_16x16x32_bf16 v[170:173], v[22:25], v[62:65], v[170:173]
	v_mfma_f32_16x16x32_bf16 v[158:161], v[14:17], v[182:185], v[158:161]
	v_mfma_f32_16x16x32_bf16 v[154:157], v[22:25], v[182:185], v[154:157]
	v_mfma_f32_16x16x32_bf16 v[142:145], v[14:17], v[208:211], v[142:145]
	v_mfma_f32_16x16x32_bf16 v[138:141], v[22:25], v[208:211], v[138:141]
	s_setprio 0
	s_setprio 1
	v_mfma_f32_16x16x32_bf16 v[6:9], v[26:29], v[50:53], 0
	v_mfma_f32_16x16x32_bf16 v[2:5], v[42:45], v[50:53], 0
	v_mfma_f32_16x16x32_bf16 v[6:9], v[30:33], v[54:57], v[6:9]
	v_mfma_f32_16x16x32_bf16 v[2:5], v[46:49], v[54:57], v[2:5]
	v_mfma_f32_16x16x32_bf16 v[50:53], v[26:29], v[58:61], 0
	v_mfma_f32_16x16x32_bf16 v[54:57], v[42:45], v[58:61], 0
	v_mfma_f32_16x16x32_bf16 v[134:137], v[26:29], v[198:201], 0
	v_mfma_f32_16x16x32_bf16 v[130:133], v[42:45], v[198:201], 0
	v_mfma_f32_16x16x32_bf16 v[50:53], v[30:33], v[62:65], v[50:53]
	v_mfma_f32_16x16x32_bf16 v[54:57], v[46:49], v[62:65], v[54:57]
	v_mfma_f32_16x16x32_bf16 v[58:61], v[26:29], v[178:181], 0
	v_mfma_f32_16x16x32_bf16 v[62:65], v[42:45], v[178:181], 0
	v_mfma_f32_16x16x32_bf16 v[134:137], v[30:33], v[208:211], v[134:137]
	v_mfma_f32_16x16x32_bf16 v[130:133], v[46:49], v[208:211], v[130:133]
	v_mfma_f32_16x16x32_bf16 v[58:61], v[30:33], v[182:185], v[58:61]
	v_mfma_f32_16x16x32_bf16 v[62:65], v[46:49], v[182:185], v[62:65]
	s_barrier
	s_setprio 0
	s_mov_b32 m0, s50
	v_lshl_add_u64 v[202:203], s[12:13], 0, v[188:189]
	s_add_u32 s56, s12, 0x20000
	s_addc_u32 s57, s13, 0
	ds_read_b128 v[146:149], v217 offset:16384
	ds_read_b128 v[150:153], v217 offset:17408
	ds_read_b128 v[162:165], v217 offset:18432
	ds_read_b128 v[166:169], v217 offset:19456
	ds_read_b128 v[178:181], v217 offset:20480
	ds_read_b128 v[182:185], v217 offset:21504
	ds_read_b128 v[198:201], v217 offset:22528
	ds_read_b128 v[208:211], v217 offset:23552
	s_cmp_lg_u32 s100, 0
	s_cbranch_scc1 .Ltl_qp_0s_p
	global_load_lds_dwordx4 v188, s[12:13]
	v_lshl_add_u64 v[204:205], s[12:13], 0, v[192:193]
	s_mov_b32 m0, s51
	s_nop 0
	global_load_lds_dwordx4 v192, s[12:13]
	s_mov_b32 m0, s59
	v_lshl_add_u64 v[222:223], s[34:35], 0, v[190:191]
	global_load_lds_dwordx4 v188, s[56:57]
	s_mov_b32 m0, s60
	s_nop 0
	global_load_lds_dwordx4 v192, s[56:57]
	v_lshl_add_u64 v[206:207], s[34:35], 0, v[186:187]
	s_mov_b32 m0, s62
	s_nop 0
	global_load_lds_dwordx4 v186, s[34:35]
	s_mov_b32 m0, s63
	s_nop 0
	global_load_lds_dwordx4 v190, s[34:35]
	s_waitcnt vmcnt(8)
	s_branch .Ltl_qp_0d_p

; #define PG8_BAR __builtin_amdgcn_s_barrier()
;     ...
;         cur = nxt; cA = nA; cB = nB; ++ui; cur.par = ui & 1;
;         if constexpr (ALIGN_EPI) { if (wr == 1) PG8_BAR; }
.LBB0_1387:
	s_or_b64 exec, exec, s[2:3]
	s_andn2_b64 vcc, exec, s[4:5]
	s_mov_b64 s[2:3], -1
	s_cbranch_vccnz .LBB0_1188
	s_andn2_b64 vcc, exec, s[14:15]
	s_cbranch_vccnz .LBB0_1187
	s_branch .LBB0_1187

;     __device__ __forceinline__ size_t aoff(const Unit& u) const { return (size_t)u.pm * bm * lda * 2; }
;     __device__ __forceinline__ size_t boff(const Unit& u) const { return (size_t)u.pn * BM * ldb * 2; }
;     __device__ __forceinline__ size_t aoff(const Unit& u) const { return ((size_t)u.pm * BM * lda + (size_t)u.pn * akoff) * 2; }
;     __device__ __forceinline__ size_t boff(const Unit& u) const { return (size_t)u.pn * BM * ldb * 2; }
;     __device__ __forceinline__ size_t aoff(const Unit& u) const { return ((size_t)u.pm * BM * lda + (size_t)(u.pn >> 1) * akoff) * 2; }
;     __device__ __forceinline__ size_t boff(const Unit& u) const { return (size_t)u.pn * BM * ldb * 2; }
; #define PG8_STAGE(bufoff, gbase, voff) do { _Pragma("unroll") for (int _i = 0; _i < 2; ++_i) \
;         __builtin_amdgcn_global_load_lds((const unsigned*)((const char*)(gbase) + (voff)[_i]), (LAS unsigned*)(lds + (bufoff) + ldsw + _i * 8192), 16, 0, 0); } while (0)
; #define PG8_LDB(dst, b, h) do { _Pragma("unroll") for (int n = 0; n < 2; ++n) _Pragma("unroll") for (int k = 0; k < 2; ++k) dst[n][k] = *(const LAS bf16x8*)(lds + PG8_SB(b, h) + boff + n * 2048 + k * 1024); } while (0)
;     ...
;         const bool has_next = S.next(ui + 1, nxt);
;         const char* nA = has_next ? (const char*)g.A + S.aoff(nxt) : cA; const char* nB = has_next ? (const char*)g.Bt + S.boff(nxt) : cB;
;         if constexpr (Epi::PRE) E.pre(lds, cur, wid);
;         for (int t = 0; t < nt; t += 2) {
;             const bool last = (t == nt - 2);
;             const char* a1 = cA + (size_t)(t + 1) * kstep;
;             const char* a2 = last ? nA : cA + (size_t)(t + 2) * kstep; const char* b2 = last ? nB : cB + (size_t)(t + 2) * kstep;
;             const char* a3 = a2 + kstep; const char* b3 = b2 + kstep;
;             if constexpr (SP2) {
;             PG8_LDB(B0, 0, 0); PG8_LDB(B1, 0, 1); PG8_SCHED; PG8_LDA(At, 0, 0); PG8_STAGE(PG8_SA(1, 1), a1 + hstepA, voffA);
;             PG8_WAIT_V(8); PG8_WAIT_L(0); PG8_BAR; PG8_MMA(0, 0, At, B0); PG8_MMA(0, 1, At, B1); PG8_BAR; PG8_SCHED;
;             PG8_LDA(At, 0, 1); PG8_STAGE(PG8_SB(0, 0), b2, voffB); PG8_STAGE(PG8_SB(0, 1), b2 + hstepB, voffB); PG8_STAGE(PG8_SA(0, 0), a2, voffA);
;             PG8_WAIT_V(8); PG8_WAIT_L(0); PG8_BAR; PG8_MMA(1, 0, At, B0); PG8_MMA(1, 1, At, B1); PG8_BAR; PG8_SCHED;
;     ...
;         if constexpr (ALIGN_EPI) { if (wr == 1) PG8_BAR; }
.LBB0_1453:
	s_ashr_i32 s15, s14, 31
	s_lshl_b64 s[2:3], s[14:15], 18
	s_add_u32 s18, s29, s2
	s_addc_u32 s19, s30, s3
	s_and_b64 s[2:3], s[6:7], exec
	s_cselect_b32 s2, s19, s23
	s_cselect_b32 s3, s18, s22
	s_add_u32 s15, s22, 0x100
	s_addc_u32 s60, s23, 0
	s_mov_b32 s73, -2
	s_cmp_lt_u32 s69, 2
	s_cbranch_scc1 .Lyb_kv
	s_cmp_eq_u64 s[12:13], 0
	s_cbranch_scc0 .Lyb_kv
	s_barrier
.Lyb_kv:
	v_add_u32_e32 v140, s31, v142
	ds_read_b128 v[144:147], v140
	ds_read_b128 v[148:151], v140 offset:1024
	ds_read_b128 v[152:155], v140 offset:2048
	ds_read_b128 v[156:159], v140 offset:3072
	v_add_u32_e32 v140, s35, v142
	ds_read_b128 v[160:163], v140
	ds_read_b128 v[164:167], v140 offset:1024
	ds_read_b128 v[168:171], v140 offset:2048
	ds_read_b128 v[172:175], v140 offset:3072
	s_add_u32 s6, s20, 0x100
	s_addc_u32 s7, s21, 0
	s_cmp_eq_u32 s73, 4
	s_cselect_b32 s25, s17, s7
	s_cselect_b32 s24, s16, s6
	s_cselect_b32 s23, s2, s60
	s_cselect_b32 s22, s3, s15
	s_cselect_b32 s100, -1, 0
	s_andn2_b32 s100, s100, s101
	s_add_i32 m0, s45, 0xc000
	ds_read_b128 v[176:179], v143
	ds_read_b128 v[180:183], v143 offset:1024
	ds_read_b128 v[184:187], v143 offset:2048
	ds_read_b128 v[188:191], v143 offset:3072
	ds_read_b128 v[192:195], v143 offset:4096
	ds_read_b128 v[196:199], v143 offset:5120
	ds_read_b128 v[200:203], v143 offset:6144
	ds_read_b128 v[208:211], v143 offset:7168
	global_load_lds_dwordx4 v136, s[20:21]
	s_add_i32 m0, s45, 0xe000
	s_nop 0
	global_load_lds_dwordx4 v138, s[20:21]
	s_waitcnt vmcnt(8)
	s_waitcnt lgkmcnt(0)
	s_setprio 1
	s_barrier
	v_mfma_f32_16x16x32_bf16 v[126:129], v[144:147], v[176:179], 0
	v_mfma_f32_16x16x32_bf16 v[122:125], v[152:155], v[176:179], 0
	v_mfma_f32_16x16x32_bf16 v[118:121], v[144:147], v[184:187], 0
	v_mfma_f32_16x16x32_bf16 v[114:117], v[152:155], v[184:187], 0
	v_mfma_f32_16x16x32_bf16 v[110:113], v[144:147], v[192:195], 0
	v_mfma_f32_16x16x32_bf16 v[106:109], v[152:155], v[192:195], 0
	v_mfma_f32_16x16x32_bf16 v[102:105], v[144:147], v[200:203], 0
	v_mfma_f32_16x16x32_bf16 v[98:101], v[152:155], v[200:203], 0
	v_mfma_f32_16x16x32_bf16 v[126:129], v[148:151], v[180:183], v[126:129]
	v_mfma_f32_16x16x32_bf16 v[122:125], v[156:159], v[180:183], v[122:125]
	v_mfma_f32_16x16x32_bf16 v[118:121], v[148:151], v[188:191], v[118:121]
	v_mfma_f32_16x16x32_bf16 v[114:117], v[156:159], v[188:191], v[114:117]
	v_mfma_f32_16x16x32_bf16 v[110:113], v[148:151], v[196:199], v[110:113]
	v_mfma_f32_16x16x32_bf16 v[106:109], v[156:159], v[196:199], v[106:109]
	v_mfma_f32_16x16x32_bf16 v[102:105], v[148:151], v[208:211], v[102:105]
	v_mfma_f32_16x16x32_bf16 v[98:101], v[156:159], v[208:211], v[98:101]
	s_setprio 0
	s_setprio 1
	v_mfma_f32_16x16x32_bf16 v[62:65], v[160:163], v[176:179], 0
	v_mfma_f32_16x16x32_bf16 v[58:61], v[168:171], v[176:179], 0
	v_mfma_f32_16x16x32_bf16 v[54:57], v[160:163], v[184:187], 0
	v_mfma_f32_16x16x32_bf16 v[50:53], v[168:171], v[184:187], 0
	v_mfma_f32_16x16x32_bf16 v[46:49], v[160:163], v[192:195], 0
	v_mfma_f32_16x16x32_bf16 v[42:45], v[168:171], v[192:195], 0
	v_mfma_f32_16x16x32_bf16 v[38:41], v[160:163], v[200:203], 0
	v_mfma_f32_16x16x32_bf16 v[34:37], v[168:171], v[200:203], 0
	v_mfma_f32_16x16x32_bf16 v[62:65], v[164:167], v[180:183], v[62:65]
	v_mfma_f32_16x16x32_bf16 v[58:61], v[172:175], v[180:183], v[58:61]
	v_mfma_f32_16x16x32_bf16 v[54:57], v[164:167], v[188:191], v[54:57]
	v_mfma_f32_16x16x32_bf16 v[50:53], v[172:175], v[188:191], v[50:53]
	v_mfma_f32_16x16x32_bf16 v[46:49], v[164:167], v[196:199], v[46:49]
	v_mfma_f32_16x16x32_bf16 v[42:45], v[172:175], v[196:199], v[42:45]
	v_mfma_f32_16x16x32_bf16 v[38:41], v[164:167], v[208:211], v[38:41]
	v_mfma_f32_16x16x32_bf16 v[34:37], v[172:175], v[208:211], v[34:37]
	s_barrier
	s_setprio 0
	s_mov_b32 m0, s33
	v_lshl_add_u64 v[140:141], s[22:23], 0, v[0:1]
	s_add_u32 s20, s22, 0x20000
	s_addc_u32 s21, s23, 0
	ds_read_b128 v[176:179], v143 offset:16384
	ds_read_b128 v[180:183], v143 offset:17408
	ds_read_b128 v[184:187], v143 offset:18432
	ds_read_b128 v[188:191], v143 offset:19456
	ds_read_b128 v[192:195], v143 offset:20480
	ds_read_b128 v[196:199], v143 offset:21504
	ds_read_b128 v[200:203], v143 offset:22528
	ds_read_b128 v[208:211], v143 offset:23552
	s_cmp_lg_u32 s100, 0
	s_cbranch_scc1 .Ltl_kv_0s_p
	global_load_lds_dwordx4 v0, s[22:23]
	v_lshl_add_u64 v[204:205], s[22:23], 0, v[134:135]
	s_mov_b32 m0, s34
	s_nop 0
	global_load_lds_dwordx4 v134, s[22:23]
	s_mov_b32 m0, s43
	v_lshl_add_u64 v[212:213], s[24:25], 0, v[132:133]
	global_load_lds_dwordx4 v0, s[20:21]
	s_mov_b32 m0, s44
	s_nop 0
	global_load_lds_dwordx4 v134, s[20:21]
	v_lshl_add_u64 v[206:207], s[24:25], 0, v[130:131]
	s_mov_b32 m0, s45
	s_nop 0
	global_load_lds_dwordx4 v130, s[24:25]
	s_mov_b32 m0, s47
	s_nop 0
	global_load_lds_dwordx4 v132, s[24:25]
	s_waitcnt vmcnt(8)
	s_branch .Ltl_kv_0d_p

; #define PG8_BAR __builtin_amdgcn_s_barrier()
; #define EPI_ROWS(u) { const int _l = lane_id(); fr = _l & 15; fq = _l >> 4; } const int row0 = (u).pm * 256 + wr * 64 + fr
; __device__ __forceinline__ u32x4 pack8(const f32x4 a, const f32x4 b) { u32x4 w; w.x = cvt_pk_bf16(a[0], a[1]); w.y = cvt_pk_bf16(a[2], a[3]); w.z = cvt_pk_bf16(b[0], b[1]); w.w = cvt_pk_bf16(b[2], b[3]); return w; }
;     ...
;         cur = nxt; cA = nA; cB = nB; ++ui; cur.par = ui & 1;
;         if constexpr (ALIGN_EPI) { if (wr == 1) PG8_BAR; }
;     __device__ __forceinline__ void operator()(const f32x4 (&acc)[2][2][4][2], const pg8::Unit& u, int wr, int wc, int fr, int fq) const {
;         EPI_ROWS(u); const int cl = wc * 32 + 8 * fq;
; #pragma unroll
;         for (int bj = 0; bj < 2; ++bj) {
;             bf16_t* base; size_t ldc;
;             if (MODE == 0) { if (u.pn < 4) { base = (bf16_t*)(ws + WS_KP) + (2 * u.pn + bj) * QKD; ldc = HEADS * QKD; } else { base = (bf16_t*)(ws + WS_VP) + (u.pn - 4) * 256 + bj * 128; ldc = HEADS * VD; } }
;             else if (MODE == 1) { base = (bf16_t*)(ws + WS_QS) + (u.pn >> 1) * KVW + (u.pn & 1) * 256 + bj * 128; ldc = HEADS * KVW; }
;             else if (MODE == 2) { base = (bf16_t*)(ws + WS_YCAT) + 1024 + u.pn * 256 + bj * 128; ldc = DM; }
;             else { base = (bf16_t*)(ws + WS_YCAT) + (size_t)MP * DM + u.pn * 256 + bj * 128; ldc = DM; }
; #pragma unroll
;             for (int ai = 0; ai < 2; ++ai)
; #pragma unroll
;                 for (int m = 0; m < 4; ++m) *(u32x4*)(base + (size_t)EPI_ROW(ai, m) * ldc + cl) = pack8(acc[ai][bj][m][0], acc[ai][bj][m][1]);
.LBB0_1465:
	v_lshl_add_u64 v[68:69], v[140:141], 1, s[2:3]
	v_cvt_pk_bf16_f32 v62, v62, v63
	v_cvt_pk_bf16_f32 v63, v64, v65
	v_cvt_pk_bf16_f32 v64, v58, v59
	v_mad_i64_i32 v[58:59], s[2:3], s6, v144, 0
	v_cvt_pk_bf16_f32 v54, v54, v55
	v_cvt_pk_bf16_f32 v55, v56, v57
	v_cvt_pk_bf16_f32 v56, v50, v51
	v_mad_i64_i32 v[50:51], s[2:3], s6, v114, 0
	v_cvt_pk_bf16_f32 v46, v46, v47
	v_cvt_pk_bf16_f32 v47, v48, v49
	v_cvt_pk_bf16_f32 v48, v42, v43
	v_mad_i64_i32 v[42:43], s[2:3], s6, v106, 0
	v_cvt_pk_bf16_f32 v38, v38, v39
	v_cvt_pk_bf16_f32 v39, v40, v41
	v_cvt_pk_bf16_f32 v40, v34, v35
	v_mad_i64_i32 v[34:35], s[2:3], s6, v99, 0
	v_cvt_pk_bf16_f32 v30, v30, v31
	v_cvt_pk_bf16_f32 v31, v32, v33
	v_cvt_pk_bf16_f32 v32, v26, v27
	v_mad_i64_i32 v[26:27], s[2:3], s6, v98, 0
	v_cvt_pk_bf16_f32 v22, v22, v23
	v_cvt_pk_bf16_f32 v23, v24, v25
	v_cvt_pk_bf16_f32 v24, v18, v19
	v_mad_i64_i32 v[18:19], s[2:3], s6, v82, 0
	v_cvt_pk_bf16_f32 v14, v14, v15
	v_cvt_pk_bf16_f32 v15, v16, v17
	v_cvt_pk_bf16_f32 v16, v10, v11
	v_mad_i64_i32 v[10:11], s[2:3], s6, v74, 0
	v_cvt_pk_bf16_f32 v6, v6, v7
	v_cvt_pk_bf16_f32 v7, v8, v9
	v_cvt_pk_bf16_f32 v8, v2, v3
	v_mad_i64_i32 v[2:3], s[2:3], s6, v66, 0
	v_cvt_pk_bf16_f32 v65, v60, v61
	v_lshl_add_u64 v[58:59], v[58:59], 1, v[68:69]
	v_cvt_pk_bf16_f32 v57, v52, v53
	v_lshl_add_u64 v[50:51], v[50:51], 1, v[68:69]
	v_cvt_pk_bf16_f32 v49, v44, v45
	v_lshl_add_u64 v[42:43], v[42:43], 1, v[68:69]
	v_cvt_pk_bf16_f32 v41, v36, v37
	v_lshl_add_u64 v[34:35], v[34:35], 1, v[68:69]
	v_cvt_pk_bf16_f32 v33, v28, v29
	v_lshl_add_u64 v[26:27], v[26:27], 1, v[68:69]
	v_cvt_pk_bf16_f32 v25, v20, v21
	v_lshl_add_u64 v[18:19], v[18:19], 1, v[68:69]
	v_cvt_pk_bf16_f32 v17, v12, v13
	v_lshl_add_u64 v[10:11], v[10:11], 1, v[68:69]
	v_cvt_pk_bf16_f32 v9, v4, v5
	v_lshl_add_u64 v[2:3], v[2:3], 1, v[68:69]
	s_and_b64 vcc, exec, s[4:5]
	s_mov_b64 s[2:3], -1
	global_store_dwordx4 v[58:59], v[62:65], off
	global_store_dwordx4 v[50:51], v[54:57], off
	global_store_dwordx4 v[42:43], v[46:49], off
	global_store_dwordx4 v[34:35], v[38:41], off
	global_store_dwordx4 v[26:27], v[30:33], off
	global_store_dwordx4 v[18:19], v[22:25], off
	global_store_dwordx4 v[10:11], v[14:17], off
	global_store_dwordx4 v[2:3], v[6:9], off
	s_cbranch_vccnz .LBB0_1444
	s_andn2_b64 vcc, exec, s[10:11]
	s_cbranch_vccnz .LBB0_1443
	s_branch .LBB0_1443

;     __device__ __forceinline__ size_t aoff(const Unit& u) const { return (size_t)u.pm * bm * lda * 2; }
;     __device__ __forceinline__ size_t boff(const Unit& u) const { return (size_t)u.pn * BM * ldb * 2; }
;     __device__ __forceinline__ size_t aoff(const Unit& u) const { return ((size_t)u.pm * BM * lda + (size_t)u.pn * akoff) * 2; }
;     __device__ __forceinline__ size_t boff(const Unit& u) const { return (size_t)u.pn * BM * ldb * 2; }
;     __device__ __forceinline__ size_t aoff(const Unit& u) const { return ((size_t)u.pm * BM * lda + (size_t)(u.pn >> 1) * akoff) * 2; }
;     __device__ __forceinline__ size_t boff(const Unit& u) const { return (size_t)u.pn * BM * ldb * 2; }
; #define PG8_STAGE(bufoff, gbase, voff) do { _Pragma("unroll") for (int _i = 0; _i < 2; ++_i) \
;         __builtin_amdgcn_global_load_lds((const unsigned*)((const char*)(gbase) + (voff)[_i]), (LAS unsigned*)(lds + (bufoff) + ldsw + _i * 8192), 16, 0, 0); } while (0)
; #define PG8_LDA(dst, b, h) do { _Pragma("unroll") for (int m = 0; m < NM; ++m) _Pragma("unroll") for (int k = 0; k < 2; ++k) dst[m][k] = *(const LAS bf16x8*)(lds + PG8_SA(b, h) + aoff + m * 2048 + k * 1024); } while (0)
; #define PG8_LDB(dst, b, h) do { _Pragma("unroll") for (int n = 0; n < 2; ++n) _Pragma("unroll") for (int k = 0; k < 2; ++k) dst[n][k] = *(const LAS bf16x8*)(lds + PG8_SB(b, h) + boff + n * 2048 + k * 1024); } while (0)
; #define PG8_BAR __builtin_amdgcn_s_barrier()
; #define PG8_SCHED __builtin_amdgcn_sched_barrier(0)
;     ...
;         const bool has_next = S.next(ui + 1, nxt);
;         const char* nA = has_next ? (const char*)g.A + S.aoff(nxt) : cA; const char* nB = has_next ? (const char*)g.Bt + S.boff(nxt) : cB;
;         if constexpr (Epi::PRE) E.pre(lds, cur, wid);
;         for (int t = 0; t < nt; t += 2) {
;             const bool last = (t == nt - 2);
;             const char* a1 = cA + (size_t)(t + 1) * kstep;
;             const char* a2 = last ? nA : cA + (size_t)(t + 2) * kstep; const char* b2 = last ? nB : cB + (size_t)(t + 2) * kstep;
;             const char* a3 = a2 + kstep; const char* b3 = b2 + kstep;
;             if constexpr (SP2) {
;             PG8_LDB(B0, 0, 0); PG8_LDB(B1, 0, 1); PG8_SCHED; PG8_LDA(At, 0, 0); PG8_STAGE(PG8_SA(1, 1), a1 + hstepA, voffA);
;     ...
;         if constexpr (ALIGN_EPI) { if (wr == 1) PG8_BAR; }
.LBB0_1649:
	s_ashr_i32 s15, s14, 31
	s_lshl_b64 s[2:3], s[14:15], 20
	s_add_u32 s18, s5, s2
	s_addc_u32 s19, s26, s3
	s_and_b64 s[2:3], s[8:9], exec
	s_cselect_b32 s2, s19, s23
	s_cselect_b32 s3, s18, s22
	s_add_u32 s8, s24, 0x60080
	s_addc_u32 s9, s25, 0
	s_add_u32 s15, s22, 0x100
	s_addc_u32 s58, s23, 0
	s_mov_b32 s59, -2
	s_waitcnt vmcnt(5)
	s_cmp_lt_u32 s54, 2
	s_cbranch_scc1 .Lyb_op
	s_cmp_eq_u64 s[10:11], 0
	s_cbranch_scc0 .Lyb_op
	s_barrier

; #define PG8_BAR __builtin_amdgcn_s_barrier()
;     ...
;         cur = nxt; cA = nA; cB = nB; ++ui; cur.par = ui & 1;
;         if constexpr (ALIGN_EPI) { if (wr == 1) PG8_BAR; }
.LBB0_1665:
	s_or_b64 exec, exec, s[2:3]
	s_and_b64 vcc, exec, s[6:7]
	s_mov_b64 s[2:3], -1
	s_cbranch_vccnz .LBB0_1644
	s_andn2_b64 vcc, exec, s[0:1]
	s_cbranch_vccnz .LBB0_1643
	s_branch .LBB0_1643

;     __device__ __forceinline__ size_t aoff(const Unit& u) const { return (size_t)u.pm * bm * lda * 2; }
;     __device__ __forceinline__ size_t boff(const Unit& u) const { return (size_t)u.pn * BM * ldb * 2; }
;     __device__ __forceinline__ size_t aoff(const Unit& u) const { return ((size_t)u.pm * BM * lda + (size_t)u.pn * akoff) * 2; }
;     __device__ __forceinline__ size_t boff(const Unit& u) const { return (size_t)u.pn * BM * ldb * 2; }
;     __device__ __forceinline__ size_t aoff(const Unit& u) const { return ((size_t)u.pm * BM * lda + (size_t)(u.pn >> 1) * akoff) * 2; }
;     __device__ __forceinline__ size_t boff(const Unit& u) const { return (size_t)u.pn * BM * ldb * 2; }
; #define PG8_STAGE(bufoff, gbase, voff) do { _Pragma("unroll") for (int _i = 0; _i < 2; ++_i) \
;         __builtin_amdgcn_global_load_lds((const unsigned*)((const char*)(gbase) + (voff)[_i]), (LAS unsigned*)(lds + (bufoff) + ldsw + _i * 8192), 16, 0, 0); } while (0)
; #define PG8_LDB(dst, b, h) do { _Pragma("unroll") for (int n = 0; n < 2; ++n) _Pragma("unroll") for (int k = 0; k < 2; ++k) dst[n][k] = *(const LAS bf16x8*)(lds + PG8_SB(b, h) + boff + n * 2048 + k * 1024); } while (0)
;     ...
;         const bool has_next = S.next(ui + 1, nxt);
;         const char* nA = has_next ? (const char*)g.A + S.aoff(nxt) : cA; const char* nB = has_next ? (const char*)g.Bt + S.boff(nxt) : cB;
;         if constexpr (Epi::PRE) E.pre(lds, cur, wid);
;         for (int t = 0; t < nt; t += 2) {
;             const bool last = (t == nt - 2);
;             const char* a1 = cA + (size_t)(t + 1) * kstep;
;             const char* a2 = last ? nA : cA + (size_t)(t + 2) * kstep; const char* b2 = last ? nB : cB + (size_t)(t + 2) * kstep;
;             const char* a3 = a2 + kstep; const char* b3 = b2 + kstep;
;             if constexpr (SP2) {
;             PG8_LDB(B0, 0, 0); PG8_LDB(B1, 0, 1); PG8_SCHED; PG8_LDA(At, 0, 0); PG8_STAGE(PG8_SA(1, 1), a1 + hstepA, voffA);
;             PG8_WAIT_V(8); PG8_WAIT_L(0); PG8_BAR; PG8_MMA(0, 0, At, B0); PG8_MMA(0, 1, At, B1); PG8_BAR; PG8_SCHED;
;             PG8_LDA(At, 0, 1); PG8_STAGE(PG8_SB(0, 0), b2, voffB); PG8_STAGE(PG8_SB(0, 1), b2 + hstepB, voffB); PG8_STAGE(PG8_SA(0, 0), a2, voffA);
;             PG8_WAIT_V(8); PG8_WAIT_L(0); PG8_BAR; PG8_MMA(1, 0, At, B0); PG8_MMA(1, 1, At, B1); PG8_BAR; PG8_SCHED;
;     ...
;         if constexpr (ALIGN_EPI) { if (wr == 1) PG8_BAR; }
.LBB0_1782:
	s_ashr_i32 s41, s40, 31
	s_lshl_b64 s[2:3], s[40:41], 20
	s_add_u32 s42, s33, s2
	s_addc_u32 s43, s48, s3
	s_and_b64 s[2:3], s[6:7], exec
	s_cselect_b32 s2, s43, s13
	s_cselect_b32 s3, s42, s12
	s_ashr_i32 s37, s36, 31
	s_lshl_b64 s[44:45], s[36:37], 20
	s_add_u32 s44, s60, s44
	s_addc_u32 s45, s63, s45
	s_and_b64 s[46:47], s[6:7], exec
	s_cselect_b32 s9, s45, s15
	s_cselect_b32 s11, s44, s14
	s_add_u32 s12, s12, 0x80080
	s_addc_u32 s13, s13, 0
	s_add_u32 s37, s14, 0x100
	s_addc_u32 s41, s15, 0
	s_mov_b32 vcc_lo, -2
	s_waitcnt vmcnt(5)
	s_cmp_lt_u32 s78, 2
	s_cbranch_scc1 .Lyb_up
	s_cmp_eq_u64 s[24:25], 0
	s_cbranch_scc0 .Lyb_up
	s_barrier
.Lyb_up:
	v_add_u32_e32 v0, s64, v208
	ds_read_b128 v[130:133], v0
	ds_read_b128 v[134:137], v0 offset:1024
	ds_read_b128 v[138:141], v0 offset:2048
	ds_read_b128 v[142:145], v0 offset:3072
	v_add_u32_e32 v0, s70, v208
	ds_read_b128 v[146:149], v0
	ds_read_b128 v[150:153], v0 offset:1024
	ds_read_b128 v[154:157], v0 offset:2048
	ds_read_b128 v[158:161], v0 offset:3072
	s_add_u32 s14, s12, 0xfff80080
	s_addc_u32 s15, s13, -1
	s_cmp_eq_u32 vcc_lo, 28
	s_cselect_b32 s47, s2, s15
	s_cselect_b32 s46, s3, s14
	s_cselect_b32 s15, s9, s41
	s_cselect_b32 s14, s11, s37
	s_cselect_b32 s100, -1, 0
	s_andn2_b32 s100, s100, s101
	s_add_i32 m0, s73, 0xc000
	ds_read_b128 v[162:165], v209
	ds_read_b128 v[166:169], v209 offset:1024
	ds_read_b128 v[170:173], v209 offset:2048
	ds_read_b128 v[174:177], v209 offset:3072
	ds_read_b128 v[190:193], v209 offset:4096
	ds_read_b128 v[194:197], v209 offset:5120
	ds_read_b128 v[198:201], v209 offset:6144
	ds_read_b128 v[202:205], v209 offset:7168
	global_load_lds_dwordx4 v186, s[12:13]
	s_add_i32 m0, s73, 0xe000
	s_nop 0
	global_load_lds_dwordx4 v188, s[12:13]
	s_waitcnt vmcnt(8)
	s_waitcnt lgkmcnt(0)
	s_setprio 1
	s_barrier
	v_mfma_f32_16x16x32_bf16 v[126:129], v[130:133], v[162:165], 0
	v_mfma_f32_16x16x32_bf16 v[94:97], v[138:141], v[162:165], 0
	v_mfma_f32_16x16x32_bf16 v[110:113], v[130:133], v[170:173], 0
	v_mfma_f32_16x16x32_bf16 v[70:73], v[138:141], v[170:173], 0
	v_mfma_f32_16x16x32_bf16 v[106:109], v[130:133], v[190:193], 0
	v_mfma_f32_16x16x32_bf16 v[66:69], v[138:141], v[190:193], 0
	v_mfma_f32_16x16x32_bf16 v[118:121], v[130:133], v[198:201], 0
	v_mfma_f32_16x16x32_bf16 v[86:89], v[138:141], v[198:201], 0
	v_mfma_f32_16x16x32_bf16 v[126:129], v[134:137], v[166:169], v[126:129]
	v_mfma_f32_16x16x32_bf16 v[94:97], v[142:145], v[166:169], v[94:97]
	v_mfma_f32_16x16x32_bf16 v[110:113], v[134:137], v[174:177], v[110:113]
	v_mfma_f32_16x16x32_bf16 v[70:73], v[142:145], v[174:177], v[70:73]
	v_mfma_f32_16x16x32_bf16 v[106:109], v[134:137], v[194:197], v[106:109]
	v_mfma_f32_16x16x32_bf16 v[66:69], v[142:145], v[194:197], v[66:69]
	v_mfma_f32_16x16x32_bf16 v[118:121], v[134:137], v[202:205], v[118:121]
	v_mfma_f32_16x16x32_bf16 v[86:89], v[142:145], v[202:205], v[86:89]
	s_setprio 0
	s_setprio 1
	v_mfma_f32_16x16x32_bf16 v[122:125], v[146:149], v[162:165], 0
	v_mfma_f32_16x16x32_bf16 v[90:93], v[154:157], v[162:165], 0
	v_mfma_f32_16x16x32_bf16 v[102:105], v[146:149], v[170:173], 0
	v_mfma_f32_16x16x32_bf16 v[62:65], v[154:157], v[170:173], 0
	v_mfma_f32_16x16x32_bf16 v[98:101], v[146:149], v[190:193], 0
	v_mfma_f32_16x16x32_bf16 v[58:61], v[154:157], v[190:193], 0
	v_mfma_f32_16x16x32_bf16 v[114:117], v[146:149], v[198:201], 0
	v_mfma_f32_16x16x32_bf16 v[82:85], v[154:157], v[198:201], 0
	v_mfma_f32_16x16x32_bf16 v[122:125], v[150:153], v[166:169], v[122:125]
	v_mfma_f32_16x16x32_bf16 v[90:93], v[158:161], v[166:169], v[90:93]
	v_mfma_f32_16x16x32_bf16 v[102:105], v[150:153], v[174:177], v[102:105]
	v_mfma_f32_16x16x32_bf16 v[62:65], v[158:161], v[174:177], v[62:65]
	v_mfma_f32_16x16x32_bf16 v[98:101], v[150:153], v[194:197], v[98:101]
	v_mfma_f32_16x16x32_bf16 v[58:61], v[158:161], v[194:197], v[58:61]
	v_mfma_f32_16x16x32_bf16 v[114:117], v[150:153], v[202:205], v[114:117]
	v_mfma_f32_16x16x32_bf16 v[82:85], v[158:161], v[202:205], v[82:85]
	s_barrier
	s_setprio 0
	s_mov_b32 m0, s68
	s_add_u32 s22, s14, 0x80000
	s_addc_u32 s23, s15, 0
	ds_read_b128 v[162:165], v209 offset:16384
	ds_read_b128 v[166:169], v209 offset:17408
	ds_read_b128 v[170:173], v209 offset:18432
	ds_read_b128 v[174:177], v209 offset:19456
	ds_read_b128 v[190:193], v209 offset:20480
	ds_read_b128 v[194:197], v209 offset:21504
	ds_read_b128 v[198:201], v209 offset:22528
	ds_read_b128 v[202:205], v209 offset:23552
	s_cmp_lg_u32 s100, 0
	s_cbranch_scc1 .Ltl_up_0s_p
	global_load_lds_dwordx4 v180, s[14:15]
	s_mov_b32 m0, s69
	s_nop 0
	global_load_lds_dwordx4 v184, s[14:15]
	s_mov_b32 m0, s71
	s_nop 0
	global_load_lds_dwordx4 v180, s[22:23]
	s_mov_b32 m0, s72
	s_nop 0
	global_load_lds_dwordx4 v184, s[22:23]
	s_mov_b32 m0, s73
	s_nop 0
	global_load_lds_dwordx4 v178, s[46:47]
	s_mov_b32 m0, s74
	s_nop 0
	global_load_lds_dwordx4 v182, s[46:47]
	s_waitcnt vmcnt(8)
	s_branch .Ltl_up_0d_p

; __device__ __forceinline__ unsigned cvt_pk_bf16(float lo, float hi) { const f32x2 v = {lo, hi}; unsigned r = __builtin_bit_cast(unsigned, __builtin_convertvector(v, bf16x2_t)); asm volatile("" : "+v"(r)); return r; }
; __device__ __forceinline__ float silu_f(float x) { return x * __builtin_amdgcn_rcpf(1.0f + __expf(-x)); }
; __device__ __forceinline__ float dpp_ror1(float x) { return __builtin_bit_cast(float, __builtin_amdgcn_update_dpp(0, __builtin_bit_cast(int, x), 0x121, 0xf, 0xf, true)); }
; __device__ __forceinline__ float dpp_ror2(float x) { return __builtin_bit_cast(float, __builtin_amdgcn_update_dpp(0, __builtin_bit_cast(int, x), 0x122, 0xf, 0xf, true)); }
;     __device__ __forceinline__ void operator()(const f32x4 (&acc_)[2][2][4][2], const pg8::Unit& u, int wr, int wc, int fr, int fq) const {
;     ...
;                 for (int m = 0; m < 4; ++m) {
;                     f32x4 c[2];
; #pragma unroll
;                     for (int bj = 0; bj < 2; ++bj) {
;                         const f32x4 h0 = acc[ai][bj][m][eh]; f32x4 p1, p2;
; #pragma unroll
;                         for (int e = 0; e < 4; ++e) {
;                             const float r1 = dpp_ror1(h0[e]), r2 = dpp_ror2(h0[e]);
;                             p1[e] = (fr >= 1) ? r1 : pr1[bj][e]; p2[e] = (fr >= 2) ? r2 : pr2[bj][e];
;                             pr1[bj][e] = r1; pr2[bj][e] = r2;
;                         }
;                         c[bj] = bia[bj] + w[bj][0] * p2 + w[bj][1] * p1 + w[bj][2] * h0;
;                     }
;                     f32x4 o;
; #pragma unroll
;                     for (int e = 0; e < 4; ++e) o[e] = silu_f(c[0][e]) * c[1][e];
;                     pk[m].x = cvt_pk_bf16(o[0], o[1]); pk[m].y = cvt_pk_bf16(o[2], o[3]);
;                 }
; #pragma unroll
;                 for (int m = 0; m < 4; ++m) *(u32x2*)(act + (size_t)(blk0 + 16 * m + fr) * DFF + ch + 4 * eh) = pk[m];
.LBB0_1858:
	v_mov_b32_e32 v90, v192
	v_mov_b32_e32 v91, v192
	v_mov_b32_e32 v92, v193
	v_mov_b32_e32 v93, v193
	v_mov_b32_e32 v191, v190
	v_mov_b32_e32 v94, v192
	v_mov_b32_e32 v95, v192
	v_pk_mul_f32 v[22:23], v[22:23], v[90:91]
	v_pk_mul_f32 v[24:25], v[24:25], v[94:95]
	v_pk_mul_f32 v[90:91], v[10:11], v[90:91]
	v_mov_b32_e32 v192, v193
	v_pk_mul_f32 v[18:19], v[18:19], v[92:93]
	v_pk_mul_f32 v[92:93], v[6:7], v[92:93]
	v_mov_b32_e32 v6, v190
	v_mov_b32_e32 v7, v190
	v_pk_mul_f32 v[10:11], v[14:15], v[190:191]
	s_waitcnt vmcnt(0) lgkmcnt(4)
	v_cndmask_b32_e64 v0, v66, v74, s[10:11]
	v_cndmask_b32_e64 v15, v67, v75, s[10:11]
	v_cndmask_b32_e64 v74, v69, v77, s[10:11]
	s_waitcnt lgkmcnt(0)
	v_cndmask_b32_e64 v75, v70, v78, s[10:11]
	v_cndmask_b32_e64 v77, v72, v80, s[10:11]
	v_cndmask_b32_e64 v78, v73, v81, s[10:11]
	v_mov_b32_dpp v80, v22 row_ror:2 row_mask:0xf bank_mask:0xf bound_ctrl:1
	v_mov_b32_dpp v81, v23 row_ror:2 row_mask:0xf bank_mask:0xf bound_ctrl:1
	v_pk_mul_f32 v[12:13], v[12:13], v[94:95]
	v_pk_mul_f32 v[94:95], v[8:9], v[192:193]
	v_pk_mul_f32 v[8:9], v[16:17], v[6:7]
	v_cndmask_b32_e64 v17, v68, v76, s[10:11]
	v_cndmask_b32_e64 v76, v71, v79, s[10:11]
	v_mov_b32_dpp v79, v22 row_ror:1 row_mask:0xf bank_mask:0xf bound_ctrl:1
	v_cndmask_b32_e64 v14, v0, v80, s[12:13]
	v_mov_b32_dpp v0, v23 row_ror:1 row_mask:0xf bank_mask:0xf bound_ctrl:1
	v_cndmask_b32_e64 v15, v15, v81, s[12:13]
	v_mov_b32_dpp v96, v24 row_ror:1 row_mask:0xf bank_mask:0xf bound_ctrl:1
	v_mov_b32_dpp v97, v24 row_ror:2 row_mask:0xf bank_mask:0xf bound_ctrl:1
	v_mov_b32_dpp v98, v25 row_ror:2 row_mask:0xf bank_mask:0xf bound_ctrl:1
	v_pk_mul_f32 v[6:7], v[4:5], v[6:7]
	v_pk_mul_f32 v[4:5], v[2:3], v[190:191]
	v_cndmask_b32_e64 v2, v79, v66, s[10:11]
	v_cndmask_b32_e64 v3, v0, v67, s[10:11]
	v_cndmask_b32_e64 v16, v96, v68, s[10:11]
	v_cndmask_b32_e64 v66, v17, v97, s[12:13]
	v_mov_b32_dpp v68, v25 row_ror:1 row_mask:0xf bank_mask:0xf bound_ctrl:1
	v_cndmask_b32_e64 v67, v74, v98, s[12:13]
	v_pk_fma_f32 v[14:15], v[38:39], v[14:15], v[42:43]
	v_cndmask_b32_e64 v17, v68, v69, s[10:11]
	v_pk_fma_f32 v[66:67], v[40:41], v[66:67], v[44:45]
	v_pk_fma_f32 v[2:3], v[34:35], v[2:3], v[14:15]
	v_mov_b32_dpp v74, v90 row_ror:2 row_mask:0xf bank_mask:0xf bound_ctrl:1
	v_pk_fma_f32 v[16:17], v[36:37], v[16:17], v[66:67]
	v_pk_fma_f32 v[2:3], v[22:23], v[26:27], v[2:3]
	v_mov_b32_dpp v69, v90 row_ror:1 row_mask:0xf bank_mask:0xf bound_ctrl:1
	v_cndmask_b32_e64 v22, v75, v74, s[12:13]
	v_mov_b32_dpp v75, v91 row_ror:2 row_mask:0xf bank_mask:0xf bound_ctrl:1
	v_pk_fma_f32 v[14:15], v[24:25], v[28:29], v[16:17]
	v_cndmask_b32_e64 v16, v69, v70, s[10:11]
	v_mov_b32_dpp v70, v91 row_ror:1 row_mask:0xf bank_mask:0xf bound_ctrl:1
	v_cndmask_b32_e64 v23, v76, v75, s[12:13]
	v_mov_b32_dpp v76, v12 row_ror:2 row_mask:0xf bank_mask:0xf bound_ctrl:1
	v_cndmask_b32_e64 v17, v70, v71, s[10:11]
	v_mov_b32_dpp v71, v12 row_ror:1 row_mask:0xf bank_mask:0xf bound_ctrl:1
	v_cndmask_b32_e64 v66, v77, v76, s[12:13]
	v_mov_b32_dpp v77, v13 row_ror:2 row_mask:0xf bank_mask:0xf bound_ctrl:1
	v_cndmask_b32_e64 v24, v71, v72, s[10:11]
	v_mov_b32_dpp v72, v13 row_ror:1 row_mask:0xf bank_mask:0xf bound_ctrl:1
	v_cndmask_b32_e64 v67, v78, v77, s[12:13]
	v_cndmask_b32_e64 v25, v72, v73, s[10:11]
	v_pk_fma_f32 v[66:67], v[60:61], v[66:67], v[64:65]
	v_pk_fma_f32 v[22:23], v[58:59], v[22:23], v[62:63]
	v_pk_fma_f32 v[24:25], v[48:49], v[24:25], v[66:67]
	v_pk_fma_f32 v[16:17], v[46:47], v[16:17], v[22:23]
	v_mul_f32_e32 v22, 0xbfb8aa3b, v2
	v_mul_f32_e32 v23, 0xbfb8aa3b, v3
	v_pk_fma_f32 v[12:13], v[12:13], v[32:33], v[24:25]
	v_mul_f32_e32 v24, 0xbfb8aa3b, v14
	v_mul_f32_e32 v25, 0xbfb8aa3b, v15
	v_exp_f32_e32 v22, v22
	v_exp_f32_e32 v23, v23
	v_exp_f32_e32 v24, v24
	v_exp_f32_e32 v25, v25
	v_add_f32_e32 v22, 1.0, v22
	v_add_f32_e32 v23, 1.0, v23
	v_add_f32_e32 v24, 1.0, v24
	v_add_f32_e32 v25, 1.0, v25
	v_rcp_f32_e32 v22, v22
	v_rcp_f32_e32 v23, v23
	v_rcp_f32_e32 v24, v24
	v_rcp_f32_e32 v25, v25
	v_pk_fma_f32 v[16:17], v[90:91], v[30:31], v[16:17]
	v_pk_mul_f32 v[2:3], v[2:3], v[22:23]
	v_pk_mul_f32 v[20:21], v[20:21], v[192:193]
	v_pk_mul_f32 v[14:15], v[14:15], v[24:25]
	v_pk_mul_f32 v[2:3], v[2:3], v[16:17]
	v_pk_mul_f32 v[12:13], v[14:15], v[12:13]
	v_mov_b32_dpp v24, v18 row_ror:1 row_mask:0xf bank_mask:0xf bound_ctrl:1
	v_mov_b32_dpp v25, v18 row_ror:2 row_mask:0xf bank_mask:0xf bound_ctrl:1
	v_mov_b32_dpp v67, v19 row_ror:2 row_mask:0xf bank_mask:0xf bound_ctrl:1
	v_cvt_pk_bf16_f32 v2, v2, v3
	v_cvt_pk_bf16_f32 v3, v12, v13
	v_cndmask_b32_e64 v12, v24, v79, s[10:11]
	v_cndmask_b32_e64 v14, v80, v25, s[12:13]
	v_mov_b32_dpp v66, v19 row_ror:1 row_mask:0xf bank_mask:0xf bound_ctrl:1
	v_cndmask_b32_e64 v15, v81, v67, s[12:13]
	v_mov_b32_dpp v73, v20 row_ror:2 row_mask:0xf bank_mask:0xf bound_ctrl:1
	v_mov_b32_dpp v79, v21 row_ror:2 row_mask:0xf bank_mask:0xf bound_ctrl:1
	v_cndmask_b32_e64 v13, v66, v0, s[10:11]
	v_mov_b32_dpp v0, v20 row_ror:1 row_mask:0xf bank_mask:0xf bound_ctrl:1
	v_cndmask_b32_e64 v22, v97, v73, s[12:13]
	v_mov_b32_dpp v78, v21 row_ror:1 row_mask:0xf bank_mask:0xf bound_ctrl:1
	v_cndmask_b32_e64 v23, v98, v79, s[12:13]
	v_pk_fma_f32 v[14:15], v[38:39], v[14:15], v[42:43]
	v_cndmask_b32_e64 v16, v0, v96, s[10:11]
	v_cndmask_b32_e64 v17, v78, v68, s[10:11]
	v_pk_fma_f32 v[22:23], v[40:41], v[22:23], v[44:45]
	v_pk_fma_f32 v[12:13], v[34:35], v[12:13], v[14:15]
	v_mov_b32_dpp v80, v92 row_ror:2 row_mask:0xf bank_mask:0xf bound_ctrl:1
	v_pk_fma_f32 v[16:17], v[36:37], v[16:17], v[22:23]
	v_pk_fma_f32 v[12:13], v[18:19], v[26:27], v[12:13]
; __device__ __forceinline__ unsigned cvt_pk_bf16(float lo, float hi) { const f32x2 v = {lo, hi}; unsigned r = __builtin_bit_cast(unsigned, __builtin_convertvector(v, bf16x2_t)); asm volatile("" : "+v"(r)); return r; }
; __device__ __forceinline__ float silu_f(float x) { return x * __builtin_amdgcn_rcpf(1.0f + __expf(-x)); }
; __device__ __forceinline__ float dpp_ror1(float x) { return __builtin_bit_cast(float, __builtin_amdgcn_update_dpp(0, __builtin_bit_cast(int, x), 0x121, 0xf, 0xf, true)); }
; __device__ __forceinline__ float dpp_ror2(float x) { return __builtin_bit_cast(float, __builtin_amdgcn_update_dpp(0, __builtin_bit_cast(int, x), 0x122, 0xf, 0xf, true)); }
;     __device__ __forceinline__ void operator()(const f32x4 (&acc_)[2][2][4][2], const pg8::Unit& u, int wr, int wc, int fr, int fq) const {
;     ...
;                 for (int m = 0; m < 4; ++m) {
;                     f32x4 c[2];
; #pragma unroll
;                     for (int bj = 0; bj < 2; ++bj) {
;                         const f32x4 h0 = acc[ai][bj][m][eh]; f32x4 p1, p2;
; #pragma unroll
;                         for (int e = 0; e < 4; ++e) {
;                             const float r1 = dpp_ror1(h0[e]), r2 = dpp_ror2(h0[e]);
;                             p1[e] = (fr >= 1) ? r1 : pr1[bj][e]; p2[e] = (fr >= 2) ? r2 : pr2[bj][e];
;                             pr1[bj][e] = r1; pr2[bj][e] = r2;
;                         }
;                         c[bj] = bia[bj] + w[bj][0] * p2 + w[bj][1] * p1 + w[bj][2] * h0;
;                     }
;                     f32x4 o;
; #pragma unroll
;                     for (int e = 0; e < 4; ++e) o[e] = silu_f(c[0][e]) * c[1][e];
;                     pk[m].x = cvt_pk_bf16(o[0], o[1]); pk[m].y = cvt_pk_bf16(o[2], o[3]);
;                 }
; #pragma unroll
;                 for (int m = 0; m < 4; ++m) *(u32x2*)(act + (size_t)(blk0 + 16 * m + fr) * DFF + ch + 4 * eh) = pk[m];
	v_mov_b32_dpp v68, v92 row_ror:1 row_mask:0xf bank_mask:0xf bound_ctrl:1
	v_cndmask_b32_e64 v18, v74, v80, s[12:13]
	v_mov_b32_dpp v74, v93 row_ror:2 row_mask:0xf bank_mask:0xf bound_ctrl:1
	v_pk_fma_f32 v[14:15], v[20:21], v[28:29], v[16:17]
	v_cndmask_b32_e64 v16, v68, v69, s[10:11]
	v_mov_b32_dpp v69, v93 row_ror:1 row_mask:0xf bank_mask:0xf bound_ctrl:1
	v_cndmask_b32_e64 v19, v75, v74, s[12:13]
	v_mov_b32_dpp v75, v94 row_ror:2 row_mask:0xf bank_mask:0xf bound_ctrl:1
	v_cndmask_b32_e64 v17, v69, v70, s[10:11]
	v_mov_b32_dpp v70, v94 row_ror:1 row_mask:0xf bank_mask:0xf bound_ctrl:1
	v_cndmask_b32_e64 v22, v76, v75, s[12:13]
	v_mov_b32_dpp v76, v95 row_ror:2 row_mask:0xf bank_mask:0xf bound_ctrl:1
	v_cndmask_b32_e64 v20, v70, v71, s[10:11]
	v_mov_b32_dpp v71, v95 row_ror:1 row_mask:0xf bank_mask:0xf bound_ctrl:1
	v_cndmask_b32_e64 v23, v77, v76, s[12:13]
	v_pk_fma_f32 v[18:19], v[58:59], v[18:19], v[62:63]
	v_cndmask_b32_e64 v21, v71, v72, s[10:11]
	v_pk_fma_f32 v[22:23], v[60:61], v[22:23], v[64:65]
	v_pk_fma_f32 v[16:17], v[46:47], v[16:17], v[18:19]
	v_mul_f32_e32 v18, 0xbfb8aa3b, v12
	v_pk_fma_f32 v[20:21], v[48:49], v[20:21], v[22:23]
	v_exp_f32_e32 v22, v18
	v_mul_f32_e32 v18, 0xbfb8aa3b, v13
	v_exp_f32_e32 v23, v18
	v_pk_fma_f32 v[18:19], v[94:95], v[32:33], v[20:21]
	v_add_f32_e32 v20, 1.0, v22
	v_mul_f32_e32 v22, 0xbfb8aa3b, v14
	v_add_f32_e32 v21, 1.0, v23
	v_mul_f32_e32 v23, 0xbfb8aa3b, v15
	v_exp_f32_e32 v22, v22
	v_exp_f32_e32 v23, v23
	v_rcp_f32_e32 v20, v20
	v_rcp_f32_e32 v21, v21
	v_add_f32_e32 v22, 1.0, v22
	v_add_f32_e32 v23, 1.0, v23
	v_rcp_f32_e32 v22, v22
	v_rcp_f32_e32 v23, v23
	v_pk_fma_f32 v[16:17], v[92:93], v[30:31], v[16:17]
	v_pk_mul_f32 v[12:13], v[12:13], v[20:21]
	v_mov_b32_dpp v72, v9 row_ror:2 row_mask:0xf bank_mask:0xf bound_ctrl:1
	v_pk_mul_f32 v[14:15], v[14:15], v[22:23]
	v_pk_mul_f32 v[12:13], v[12:13], v[16:17]
	v_pk_mul_f32 v[14:15], v[14:15], v[18:19]
	v_mov_b32_dpp v22, v10 row_ror:1 row_mask:0xf bank_mask:0xf bound_ctrl:1
	v_mov_b32_dpp v23, v10 row_ror:2 row_mask:0xf bank_mask:0xf bound_ctrl:1
	v_cvt_pk_bf16_f32 v12, v12, v13
	v_cvt_pk_bf16_f32 v13, v14, v15
	v_cndmask_b32_e64 v14, v22, v24, s[10:11]
	v_cndmask_b32_e64 v16, v25, v23, s[12:13]
	v_mov_b32_dpp v24, v11 row_ror:1 row_mask:0xf bank_mask:0xf bound_ctrl:1
	v_mov_b32_dpp v25, v11 row_ror:2 row_mask:0xf bank_mask:0xf bound_ctrl:1
	v_cndmask_b32_e64 v15, v24, v66, s[10:11]
	v_cndmask_b32_e64 v17, v67, v25, s[12:13]
	v_mov_b32_dpp v66, v8 row_ror:1 row_mask:0xf bank_mask:0xf bound_ctrl:1
	v_mov_b32_dpp v67, v8 row_ror:2 row_mask:0xf bank_mask:0xf bound_ctrl:1
	v_cndmask_b32_e64 v18, v66, v0, s[10:11]
	v_mov_b32_dpp v0, v9 row_ror:1 row_mask:0xf bank_mask:0xf bound_ctrl:1
	v_pk_fma_f32 v[16:17], v[38:39], v[16:17], v[42:43]
	v_cndmask_b32_e64 v20, v73, v67, s[12:13]
	v_cndmask_b32_e64 v19, v0, v78, s[10:11]
	v_cndmask_b32_e64 v21, v79, v72, s[12:13]
	v_pk_fma_f32 v[14:15], v[34:35], v[14:15], v[16:17]
	v_mov_b32_dpp v73, v4 row_ror:1 row_mask:0xf bank_mask:0xf bound_ctrl:1
	v_mov_b32_dpp v78, v5 row_ror:2 row_mask:0xf bank_mask:0xf bound_ctrl:1
	v_pk_fma_f32 v[20:21], v[40:41], v[20:21], v[44:45]
	v_pk_fma_f32 v[10:11], v[10:11], v[26:27], v[14:15]
	v_cndmask_b32_e64 v14, v73, v68, s[10:11]
	v_mov_b32_dpp v68, v5 row_ror:1 row_mask:0xf bank_mask:0xf bound_ctrl:1
	v_cndmask_b32_e64 v17, v74, v78, s[12:13]
	v_mov_b32_dpp v74, v6 row_ror:2 row_mask:0xf bank_mask:0xf bound_ctrl:1
	v_pk_fma_f32 v[18:19], v[36:37], v[18:19], v[20:21]
	v_cndmask_b32_e64 v15, v68, v69, s[10:11]
	v_mov_b32_dpp v69, v6 row_ror:1 row_mask:0xf bank_mask:0xf bound_ctrl:1
	v_cndmask_b32_e64 v20, v75, v74, s[12:13]
	v_mov_b32_dpp v75, v7 row_ror:2 row_mask:0xf bank_mask:0xf bound_ctrl:1
	v_pk_fma_f32 v[8:9], v[8:9], v[28:29], v[18:19]
	v_mov_b32_dpp v77, v4 row_ror:2 row_mask:0xf bank_mask:0xf bound_ctrl:1
	v_cndmask_b32_e64 v18, v69, v70, s[10:11]
	v_mov_b32_dpp v70, v7 row_ror:1 row_mask:0xf bank_mask:0xf bound_ctrl:1
	v_cndmask_b32_e64 v21, v76, v75, s[12:13]
	v_cndmask_b32_e64 v16, v80, v77, s[12:13]
	v_cndmask_b32_e64 v19, v70, v71, s[10:11]
	v_pk_fma_f32 v[20:21], v[60:61], v[20:21], v[64:65]
	v_pk_fma_f32 v[16:17], v[58:59], v[16:17], v[62:63]
	v_pk_fma_f32 v[18:19], v[48:49], v[18:19], v[20:21]
	v_pk_fma_f32 v[14:15], v[46:47], v[14:15], v[16:17]
; __device__ __forceinline__ unsigned cvt_pk_bf16(float lo, float hi) { const f32x2 v = {lo, hi}; unsigned r = __builtin_bit_cast(unsigned, __builtin_convertvector(v, bf16x2_t)); asm volatile("" : "+v"(r)); return r; }
; __device__ __forceinline__ float silu_f(float x) { return x * __builtin_amdgcn_rcpf(1.0f + __expf(-x)); }
; #define PG8_BAR __builtin_amdgcn_s_barrier()
; __device__ __forceinline__ float dpp_ror1(float x) { return __builtin_bit_cast(float, __builtin_amdgcn_update_dpp(0, __builtin_bit_cast(int, x), 0x121, 0xf, 0xf, true)); }
; __device__ __forceinline__ float dpp_ror2(float x) { return __builtin_bit_cast(float, __builtin_amdgcn_update_dpp(0, __builtin_bit_cast(int, x), 0x122, 0xf, 0xf, true)); }
;     ...
;         cur = nxt; cA = nA; cB = nB; ++ui; cur.par = ui & 1;
;         if constexpr (ALIGN_EPI) { if (wr == 1) PG8_BAR; }
;     __device__ __forceinline__ void operator()(const f32x4 (&acc_)[2][2][4][2], const pg8::Unit& u, int wr, int wc, int fr, int fq) const {
;     ...
;                 for (int m = 0; m < 4; ++m) {
;                     f32x4 c[2];
; #pragma unroll
;                     for (int bj = 0; bj < 2; ++bj) {
;                         const f32x4 h0 = acc[ai][bj][m][eh]; f32x4 p1, p2;
; #pragma unroll
;                         for (int e = 0; e < 4; ++e) {
;                             const float r1 = dpp_ror1(h0[e]), r2 = dpp_ror2(h0[e]);
;                             p1[e] = (fr >= 1) ? r1 : pr1[bj][e]; p2[e] = (fr >= 2) ? r2 : pr2[bj][e];
;                             pr1[bj][e] = r1; pr2[bj][e] = r2;
;                         }
;                         c[bj] = bia[bj] + w[bj][0] * p2 + w[bj][1] * p1 + w[bj][2] * h0;
;                     }
;                     f32x4 o;
; #pragma unroll
;                     for (int e = 0; e < 4; ++e) o[e] = silu_f(c[0][e]) * c[1][e];
;                     pk[m].x = cvt_pk_bf16(o[0], o[1]); pk[m].y = cvt_pk_bf16(o[2], o[3]);
;                 }
; #pragma unroll
;                 for (int m = 0; m < 4; ++m) *(u32x2*)(act + (size_t)(blk0 + 16 * m + fr) * DFF + ch + 4 * eh) = pk[m];
	v_mul_f32_e32 v16, 0xbfb8aa3b, v10
	v_mul_f32_e32 v17, 0xbfb8aa3b, v11
	v_pk_fma_f32 v[6:7], v[6:7], v[32:33], v[18:19]
	v_mul_f32_e32 v18, 0xbfb8aa3b, v8
	v_mul_f32_e32 v19, 0xbfb8aa3b, v9
	v_exp_f32_e32 v16, v16
	v_exp_f32_e32 v17, v17
	v_exp_f32_e32 v18, v18
	v_exp_f32_e32 v19, v19
	v_add_f32_e32 v16, 1.0, v16
	v_add_f32_e32 v17, 1.0, v17
	v_add_f32_e32 v18, 1.0, v18
	v_add_f32_e32 v19, 1.0, v19
	v_rcp_f32_e32 v16, v16
	v_rcp_f32_e32 v17, v17
	v_rcp_f32_e32 v18, v18
	v_rcp_f32_e32 v19, v19
	v_pk_fma_f32 v[4:5], v[4:5], v[30:31], v[14:15]
	v_pk_mul_f32 v[10:11], v[10:11], v[16:17]
	v_mov_b32_dpp v15, v57 row_ror:2 row_mask:0xf bank_mask:0xf bound_ctrl:1
	v_pk_mul_f32 v[8:9], v[8:9], v[18:19]
	v_pk_mul_f32 v[4:5], v[10:11], v[4:5]
	v_pk_mul_f32 v[6:7], v[8:9], v[6:7]
	v_mov_b32_dpp v11, v56 row_ror:2 row_mask:0xf bank_mask:0xf bound_ctrl:1
	v_cvt_pk_bf16_f32 v4, v4, v5
	v_cvt_pk_bf16_f32 v5, v6, v7
	v_mov_b32_dpp v7, v54 row_ror:2 row_mask:0xf bank_mask:0xf bound_ctrl:1
	v_mov_b32_dpp v9, v55 row_ror:2 row_mask:0xf bank_mask:0xf bound_ctrl:1
	v_cndmask_b32_e64 v14, v67, v11, s[12:13]
	v_mov_b32_dpp v11, v57 row_ror:1 row_mask:0xf bank_mask:0xf bound_ctrl:1
	v_mov_b32_dpp v6, v54 row_ror:1 row_mask:0xf bank_mask:0xf bound_ctrl:1
	v_cndmask_b32_e64 v8, v23, v7, s[12:13]
	v_mov_b32_dpp v7, v55 row_ror:1 row_mask:0xf bank_mask:0xf bound_ctrl:1
	v_cndmask_b32_e64 v9, v25, v9, s[12:13]
	v_cndmask_b32_e64 v11, v11, v0, s[10:11]
	v_mov_b32_dpp v0, v50 row_ror:1 row_mask:0xf bank_mask:0xf bound_ctrl:1
	v_cndmask_b32_e64 v6, v6, v22, s[10:11]
	v_cndmask_b32_e64 v7, v7, v24, s[10:11]
	v_mov_b32_dpp v17, v50 row_ror:2 row_mask:0xf bank_mask:0xf bound_ctrl:1
	v_cndmask_b32_e64 v16, v0, v73, s[10:11]
	v_mov_b32_dpp v0, v51 row_ror:1 row_mask:0xf bank_mask:0xf bound_ctrl:1
	v_pk_fma_f32 v[8:9], v[38:39], v[8:9], v[42:43]
	v_mov_b32_dpp v10, v56 row_ror:1 row_mask:0xf bank_mask:0xf bound_ctrl:1
	v_cndmask_b32_e64 v15, v72, v15, s[12:13]
	v_cndmask_b32_e64 v18, v77, v17, s[12:13]
	v_mov_b32_dpp v19, v51 row_ror:2 row_mask:0xf bank_mask:0xf bound_ctrl:1
	v_cndmask_b32_e64 v17, v0, v68, s[10:11]
	v_mov_b32_dpp v0, v52 row_ror:1 row_mask:0xf bank_mask:0xf bound_ctrl:1
	v_pk_fma_f32 v[6:7], v[34:35], v[6:7], v[8:9]
	v_cndmask_b32_e64 v10, v10, v66, s[10:11]
	v_cndmask_b32_e64 v19, v78, v19, s[12:13]
	v_mov_b32_dpp v21, v52 row_ror:2 row_mask:0xf bank_mask:0xf bound_ctrl:1
	v_cndmask_b32_e64 v20, v0, v69, s[10:11]
	v_mov_b32_dpp v0, v53 row_ror:1 row_mask:0xf bank_mask:0xf bound_ctrl:1
	v_pk_fma_f32 v[14:15], v[40:41], v[14:15], v[44:45]
	v_pk_fma_f32 v[6:7], v[54:55], v[26:27], v[6:7]
	v_cndmask_b32_e64 v22, v74, v21, s[12:13]
	v_cndmask_b32_e64 v21, v0, v70, s[10:11]
	v_pk_fma_f32 v[8:9], v[36:37], v[10:11], v[14:15]
	v_pk_fma_f32 v[14:15], v[58:59], v[18:19], v[62:63]
	v_mul_f32_e32 v0, 0xbfb8aa3b, v6
	v_pk_fma_f32 v[14:15], v[46:47], v[16:17], v[14:15]
	v_exp_f32_e32 v0, v0
	v_mul_f32_e32 v16, 0xbfb8aa3b, v7
	v_exp_f32_e32 v17, v16
	v_pk_fma_f32 v[8:9], v[56:57], v[28:29], v[8:9]
	v_add_f32_e32 v0, 1.0, v0
	v_rcp_f32_e32 v16, v0
	v_add_f32_e32 v0, 1.0, v17
	v_mul_f32_e32 v17, 0xbfb8aa3b, v8
	v_exp_f32_e32 v18, v17
	v_mul_f32_e32 v17, 0xbfb8aa3b, v9
	v_exp_f32_e32 v19, v17
	v_rcp_f32_e32 v17, v0
	v_add_f32_e32 v0, 1.0, v18
	v_rcp_f32_e32 v18, v0
	v_add_f32_e32 v0, 1.0, v19
	v_mov_b32_dpp v23, v53 row_ror:2 row_mask:0xf bank_mask:0xf bound_ctrl:1
	v_rcp_f32_e32 v19, v0
	v_cndmask_b32_e64 v23, v75, v23, s[12:13]
	v_pk_fma_f32 v[10:11], v[60:61], v[22:23], v[64:65]
	v_pk_fma_f32 v[14:15], v[50:51], v[30:31], v[14:15]
	v_pk_fma_f32 v[10:11], v[48:49], v[20:21], v[10:11]
	v_pk_mul_f32 v[6:7], v[6:7], v[16:17]
	v_pk_fma_f32 v[10:11], v[52:53], v[32:33], v[10:11]
	v_pk_mul_f32 v[8:9], v[8:9], v[18:19]
	v_pk_mul_f32 v[6:7], v[6:7], v[14:15]
	v_pk_mul_f32 v[8:9], v[8:9], v[10:11]
	v_cvt_pk_bf16_f32 v6, v6, v7
	v_cvt_pk_bf16_f32 v7, v8, v9
	s_andn2_b64 vcc, exec, s[6:7]
	s_mov_b64 s[2:3], -1
	global_store_dwordx2 v[82:83], v[2:3], off offset:8
	global_store_dwordx2 v[84:85], v[12:13], off offset:8
	global_store_dwordx2 v[86:87], v[4:5], off offset:8
	global_store_dwordx2 v[88:89], v[6:7], off offset:8
	s_cbranch_vccnz .LBB0_1769
	s_andn2_b64 vcc, exec, s[0:1]
	s_cbranch_vccnz .LBB0_1768
	s_branch .LBB0_1768

;     __device__ __forceinline__ size_t aoff(const Unit& u) const { return (size_t)u.pm * bm * lda * 2; }
;     __device__ __forceinline__ size_t boff(const Unit& u) const { return (size_t)u.pn * BM * ldb * 2; }
;     __device__ __forceinline__ size_t aoff(const Unit& u) const { return ((size_t)u.pm * BM * lda + (size_t)u.pn * akoff) * 2; }
;     __device__ __forceinline__ size_t boff(const Unit& u) const { return (size_t)u.pn * BM * ldb * 2; }
;     __device__ __forceinline__ size_t aoff(const Unit& u) const { return ((size_t)u.pm * BM * lda + (size_t)(u.pn >> 1) * akoff) * 2; }
;     __device__ __forceinline__ size_t boff(const Unit& u) const { return (size_t)u.pn * BM * ldb * 2; }
; #define PG8_STAGE(bufoff, gbase, voff) do { _Pragma("unroll") for (int _i = 0; _i < 2; ++_i) \
;         __builtin_amdgcn_global_load_lds((const unsigned*)((const char*)(gbase) + (voff)[_i]), (LAS unsigned*)(lds + (bufoff) + ldsw + _i * 8192), 16, 0, 0); } while (0)
; #define PG8_LDA(dst, b, h) do { _Pragma("unroll") for (int m = 0; m < NM; ++m) _Pragma("unroll") for (int k = 0; k < 2; ++k) dst[m][k] = *(const LAS bf16x8*)(lds + PG8_SA(b, h) + aoff + m * 2048 + k * 1024); } while (0)
; #define PG8_LDB(dst, b, h) do { _Pragma("unroll") for (int n = 0; n < 2; ++n) _Pragma("unroll") for (int k = 0; k < 2; ++k) dst[n][k] = *(const LAS bf16x8*)(lds + PG8_SB(b, h) + boff + n * 2048 + k * 1024); } while (0)
; #define PG8_BAR __builtin_amdgcn_s_barrier()
; #define PG8_SCHED __builtin_amdgcn_sched_barrier(0)
;     ...
;         const bool has_next = S.next(ui + 1, nxt);
;         const char* nA = has_next ? (const char*)g.A + S.aoff(nxt) : cA; const char* nB = has_next ? (const char*)g.Bt + S.boff(nxt) : cB;
;         if constexpr (Epi::PRE) E.pre(lds, cur, wid);
;         for (int t = 0; t < nt; t += 2) {
;             const bool last = (t == nt - 2);
;             const char* a1 = cA + (size_t)(t + 1) * kstep;
;             const char* a2 = last ? nA : cA + (size_t)(t + 2) * kstep; const char* b2 = last ? nB : cB + (size_t)(t + 2) * kstep;
;             const char* a3 = a2 + kstep; const char* b3 = b2 + kstep;
;             if constexpr (SP2) {
;             PG8_LDB(B0, 0, 0); PG8_LDB(B1, 0, 1); PG8_SCHED; PG8_LDA(At, 0, 0); PG8_STAGE(PG8_SA(1, 1), a1 + hstepA, voffA);
;     ...
;         if constexpr (ALIGN_EPI) { if (wr == 1) PG8_BAR; }
.LBB0_2157:
	s_add_u32 s2, s16, 0x100
	s_addc_u32 s3, s17, 0
	s_mov_b32 s60, -2
	s_waitcnt vmcnt(5)
	s_cmp_lt_u32 s54, 2
	s_cbranch_scc1 .Lyb_dn
	s_cmp_eq_u64 s[8:9], 0
	s_cbranch_scc0 .Lyb_dn
	s_barrier

; #define PG8_BAR __builtin_amdgcn_s_barrier()
;     ...
;         cur = nxt; cA = nA; cB = nB; ++ui; cur.par = ui & 1;
;         if constexpr (ALIGN_EPI) { if (wr == 1) PG8_BAR; }
.LBB0_2173:
	s_or_b64 exec, exec, s[2:3]
	s_and_b64 vcc, exec, s[4:5]
	s_mov_b64 s[2:3], -1
	s_cbranch_vccnz .LBB0_2150
	s_andn2_b64 vcc, exec, s[0:1]
	s_cbranch_vccnz .LBB0_2149
	s_branch .LBB0_2149
